# rwkv scans: 16-step body, 2 operand sets, y/g per-lane partials reduced once per 16 steps by bank-masked DPP transpose-reduction
# speedup vs baseline: 1.0159x; 1.0098x over previous
; template <bool DUAL>
; __device__ __forceinline__ void rwkv_tile(const Params& p, int l, int tile, unsigned char* smem) {
;     ...
; #pragma unroll 2
;       for (int i = 0; i < 32; ++i) {
;         const int inx = (i + 1) & 31;
;         const float4 nw4 = *(const float4*)(rp + inx * 384), nkk4 = *(const float4*)(rp + inx * 384 + 64), nkb4 = *(const float4*)(rp + inx * 384 + 128);
;         const float4 nkd4 = *(const float4*)(rp + inx * 384 + 192), nr4 = *(const float4*)(rp + inx * 384 + 256);
;         const float nv = vp[inx * 384];
;         v2f t = sA * (v2f){kk4.x, kk4.y};
;         t = sB * (v2f){kk4.z, kk4.w} + t;
;         float sa = t.x + t.y, ia = 0.f;
;         if (DUAL) {
;           v2f ti = iA * (v2f){kk4.x, kk4.y};
;           ti = iB * (v2f){kk4.z, kk4.w} + ti;
;           ia = ti.x + ti.y;
;           sa += dppf<0xB1>(sa); ia += dppf<0xB1>(ia);
;           sa += dppf<0x4E>(sa); ia += dppf<0x4E>(ia);
;           sa += dppf<0x141>(sa); ia += dppf<0x141>(ia);
;           sa += dppf<0x140>(sa); ia += dppf<0x140>(ia);
;         } else {
;           sa = sum16(sa);
;         }
;         v2f cA = sA * (v2f){w4.x, w4.y} + (v2f){kd4.x, kd4.y} * v;
;         v2f cB = sB * (v2f){w4.z, w4.w} + (v2f){kd4.z, kd4.w} * v;
;         sA = cA - (v2f){kb4.x, kb4.y} * sa;
;         sB = cB - (v2f){kb4.z, kb4.w} * sa;
;         v2f u = sA * (v2f){r4.x, r4.y};
;         u = sB * (v2f){r4.z, r4.w} + u;
;         float y = u.x + u.y, g = 0.f;
;         if (DUAL) {
;           iA = iA * (v2f){w4.x, w4.y} - (v2f){kb4.x, kb4.y} * ia;
;           iB = iB * (v2f){w4.z, w4.w} - (v2f){kb4.z, kb4.w} * ia;
;           v2f ui = iA * (v2f){r4.x, r4.y};
;           ui = iB * (v2f){r4.z, r4.w} + ui;
;           g = ui.x + ui.y;
;           y += dppf<0xB1>(y); g += dppf<0xB1>(g);
;           y += dppf<0x4E>(y); g += dppf<0x4E>(g);
;           y += dppf<0x141>(y); g += dppf<0x141>(g);
;           y += dppf<0x140>(y); g += dppf<0x140>(g);
.Lrw_du_scan:
	v_mov_b32_e32 v74, v102
	v_mov_b32_e32 v75, v103
	v_add_u32_e32 v69, 0x6000, v102
	v_add_u32_e32 v70, 0x6000, v103
	v_mov_b32_e32 v68, v101
	s_mov_b32 vcc_lo, 0xcccccccc
	s_mov_b32 vcc_hi, 0xcccccccc
	s_mov_b32 s100, 0xaaaaaaaa
	s_mov_b32 s101, 0xaaaaaaaa
	ds_read_b128 v[220:223], v74 offset:25600
	ds_read_b128 v[216:219], v74 offset:25344
	ds_read_b128 v[228:231], v74 offset:26112
	ds_read_b32 v236, v75 offset:26624
	ds_read_b128 v[224:227], v74 offset:25856
	ds_read_b128 v[232:235], v74 offset:26368
	ds_read_b128 v[126:129], v74 offset:27136
	ds_read_b128 v[122:125], v74 offset:26880
	ds_read_b128 v[134:137], v74 offset:27648
	ds_read_b32 v142, v75 offset:28160
	ds_read_b128 v[130:133], v74 offset:27392
	ds_read_b128 v[138:141], v74 offset:27904
	s_mov_b32 s55, 0
.Lrw_du_loop:
	s_waitcnt lgkmcnt(6)
	v_pk_mul_f32 v[60:61], v[94:95], v[220:221]
	v_pk_mul_f32 v[62:63], v[88:89], v[220:221]
	v_pk_fma_f32 v[60:61], v[92:93], v[222:223], v[60:61]
	v_pk_fma_f32 v[62:63], v[90:91], v[222:223], v[62:63]
	v_add_f32_e32 v60, v60, v61
	v_add_f32_e32 v62, v62, v63
	v_pk_mul_f32 v[94:95], v[94:95], v[216:217]
	v_pk_mul_f32 v[92:93], v[92:93], v[218:219]
	v_add_f32_dpp v60, v60, v60 quad_perm:[1,0,3,2] row_mask:0xf bank_mask:0xf bound_ctrl:1
	v_add_f32_dpp v62, v62, v62 quad_perm:[1,0,3,2] row_mask:0xf bank_mask:0xf bound_ctrl:1
	v_pk_fma_f32 v[94:95], v[236:237], v[228:229], v[94:95] op_sel_hi:[0,1,1]
	v_add_f32_dpp v60, v60, v60 quad_perm:[2,3,0,1] row_mask:0xf bank_mask:0xf bound_ctrl:1
	v_add_f32_dpp v62, v62, v62 quad_perm:[2,3,0,1] row_mask:0xf bank_mask:0xf bound_ctrl:1
	v_pk_fma_f32 v[92:93], v[236:237], v[230:231], v[92:93] op_sel_hi:[0,1,1]
	v_add_f32_dpp v60, v60, v60 row_half_mirror row_mask:0xf bank_mask:0xf bound_ctrl:1
	v_add_f32_dpp v62, v62, v62 row_half_mirror row_mask:0xf bank_mask:0xf bound_ctrl:1
	ds_read_b128 v[220:223], v74 offset:28672
	v_add_f32_dpp v60, v60, v60 row_mirror row_mask:0xf bank_mask:0xf bound_ctrl:1
	v_add_f32_dpp v62, v62, v62 row_mirror row_mask:0xf bank_mask:0xf bound_ctrl:1
	ds_read_b128 v[228:231], v74 offset:29184
	ds_read_b32 v236, v75 offset:29696
	v_pk_fma_f32 v[94:95], v[224:225], v[60:61], v[94:95] op_sel_hi:[1,0,1] neg_lo:[1,0,0] neg_hi:[1,0,0]
	v_pk_fma_f32 v[92:93], v[226:227], v[60:61], v[92:93] op_sel_hi:[1,0,1] neg_lo:[1,0,0] neg_hi:[1,0,0]
	v_pk_mul_f32 v[238:239], v[224:225], v[62:63] op_sel_hi:[1,0]
	v_pk_mul_f32 v[240:241], v[226:227], v[62:63] op_sel_hi:[1,0]
	ds_read_b128 v[224:227], v74 offset:28928
	v_pk_mul_f32 v[64:65], v[232:233], v[94:95]
	v_pk_fma_f32 v[88:89], v[88:89], v[216:217], v[238:239] neg_lo:[0,0,1] neg_hi:[0,0,1]
	v_pk_fma_f32 v[90:91], v[90:91], v[218:219], v[240:241] neg_lo:[0,0,1] neg_hi:[0,0,1]
	ds_read_b128 v[216:219], v74 offset:28416
	v_pk_fma_f32 v[64:65], v[234:235], v[92:93], v[64:65]
	v_pk_mul_f32 v[66:67], v[232:233], v[88:89]
	v_pk_fma_f32 v[66:67], v[234:235], v[90:91], v[66:67]
	ds_read_b128 v[232:235], v74 offset:29440
	v_add_f32_e32 v144, v64, v65
	v_add_f32_e32 v165, v66, v67
	s_waitcnt lgkmcnt(6)
	v_pk_mul_f32 v[60:61], v[94:95], v[126:127]
	v_pk_mul_f32 v[62:63], v[88:89], v[126:127]
	v_pk_fma_f32 v[60:61], v[92:93], v[128:129], v[60:61]
	v_pk_fma_f32 v[62:63], v[90:91], v[128:129], v[62:63]
	v_add_f32_e32 v60, v60, v61
	v_add_f32_e32 v62, v62, v63
	v_pk_mul_f32 v[94:95], v[94:95], v[122:123]
	v_pk_mul_f32 v[92:93], v[92:93], v[124:125]
	v_add_f32_dpp v60, v60, v60 quad_perm:[1,0,3,2] row_mask:0xf bank_mask:0xf bound_ctrl:1
	v_add_f32_dpp v62, v62, v62 quad_perm:[1,0,3,2] row_mask:0xf bank_mask:0xf bound_ctrl:1
	v_pk_fma_f32 v[94:95], v[142:143], v[134:135], v[94:95] op_sel_hi:[0,1,1]
	v_add_f32_dpp v60, v60, v60 quad_perm:[2,3,0,1] row_mask:0xf bank_mask:0xf bound_ctrl:1
	v_add_f32_dpp v62, v62, v62 quad_perm:[2,3,0,1] row_mask:0xf bank_mask:0xf bound_ctrl:1
	v_pk_fma_f32 v[92:93], v[142:143], v[136:137], v[92:93] op_sel_hi:[0,1,1]
	v_add_f32_dpp v60, v60, v60 row_half_mirror row_mask:0xf bank_mask:0xf bound_ctrl:1
	v_add_f32_dpp v62, v62, v62 row_half_mirror row_mask:0xf bank_mask:0xf bound_ctrl:1
	ds_read_b128 v[126:129], v74 offset:30208
	v_add_f32_dpp v60, v60, v60 row_mirror row_mask:0xf bank_mask:0xf bound_ctrl:1
	v_add_f32_dpp v62, v62, v62 row_mirror row_mask:0xf bank_mask:0xf bound_ctrl:1
	ds_read_b128 v[134:137], v74 offset:30720
	ds_read_b32 v142, v75 offset:31232
	v_pk_fma_f32 v[94:95], v[130:131], v[60:61], v[94:95] op_sel_hi:[1,0,1] neg_lo:[1,0,0] neg_hi:[1,0,0]
	v_pk_fma_f32 v[92:93], v[132:133], v[60:61], v[92:93] op_sel_hi:[1,0,1] neg_lo:[1,0,0] neg_hi:[1,0,0]
	v_pk_mul_f32 v[238:239], v[130:131], v[62:63] op_sel_hi:[1,0]
	v_pk_mul_f32 v[240:241], v[132:133], v[62:63] op_sel_hi:[1,0]
	ds_read_b128 v[130:133], v74 offset:30464
	v_pk_mul_f32 v[64:65], v[138:139], v[94:95]
	v_pk_fma_f32 v[88:89], v[88:89], v[122:123], v[238:239] neg_lo:[0,0,1] neg_hi:[0,0,1]
	v_pk_fma_f32 v[90:91], v[90:91], v[124:125], v[240:241] neg_lo:[0,0,1] neg_hi:[0,0,1]
	ds_read_b128 v[122:125], v74 offset:29952
	v_pk_fma_f32 v[64:65], v[140:141], v[92:93], v[64:65]
	v_pk_mul_f32 v[66:67], v[138:139], v[88:89]
	v_pk_fma_f32 v[66:67], v[140:141], v[90:91], v[66:67]
	ds_read_b128 v[138:141], v74 offset:30976
	v_add_f32_e32 v145, v64, v65
	v_add_f32_e32 v166, v66, v67
	s_waitcnt lgkmcnt(6)
; template <bool DUAL>
; __device__ __forceinline__ void rwkv_tile(const Params& p, int l, int tile, unsigned char* smem) {
;     ...
;       for (int i = 0; i < 32; ++i) {
;         const int inx = (i + 1) & 31;
;         const float4 nw4 = *(const float4*)(rp + inx * 384), nkk4 = *(const float4*)(rp + inx * 384 + 64), nkb4 = *(const float4*)(rp + inx * 384 + 128);
;         const float4 nkd4 = *(const float4*)(rp + inx * 384 + 192), nr4 = *(const float4*)(rp + inx * 384 + 256);
;         const float nv = vp[inx * 384];
;         v2f t = sA * (v2f){kk4.x, kk4.y};
;         t = sB * (v2f){kk4.z, kk4.w} + t;
;         float sa = t.x + t.y, ia = 0.f;
;         if (DUAL) {
;           v2f ti = iA * (v2f){kk4.x, kk4.y};
;           ti = iB * (v2f){kk4.z, kk4.w} + ti;
;           ia = ti.x + ti.y;
;           sa += dppf<0xB1>(sa); ia += dppf<0xB1>(ia);
;           sa += dppf<0x4E>(sa); ia += dppf<0x4E>(ia);
;           sa += dppf<0x141>(sa); ia += dppf<0x141>(ia);
;           sa += dppf<0x140>(sa); ia += dppf<0x140>(ia);
;         } else {
;           sa = sum16(sa);
;         }
;         v2f cA = sA * (v2f){w4.x, w4.y} + (v2f){kd4.x, kd4.y} * v;
;         v2f cB = sB * (v2f){w4.z, w4.w} + (v2f){kd4.z, kd4.w} * v;
;         sA = cA - (v2f){kb4.x, kb4.y} * sa;
;         sB = cB - (v2f){kb4.z, kb4.w} * sa;
;         v2f u = sA * (v2f){r4.x, r4.y};
;         u = sB * (v2f){r4.z, r4.w} + u;
;         float y = u.x + u.y, g = 0.f;
;         if (DUAL) {
;           iA = iA * (v2f){w4.x, w4.y} - (v2f){kb4.x, kb4.y} * ia;
;           iB = iB * (v2f){w4.z, w4.w} - (v2f){kb4.z, kb4.w} * ia;
;           v2f ui = iA * (v2f){r4.x, r4.y};
;           ui = iB * (v2f){r4.z, r4.w} + ui;
;           g = ui.x + ui.y;
;           y += dppf<0xB1>(y); g += dppf<0xB1>(g);
;           y += dppf<0x4E>(y); g += dppf<0x4E>(g);
;           y += dppf<0x141>(y); g += dppf<0x141>(g);
;           y += dppf<0x140>(y); g += dppf<0x140>(g);
	v_pk_mul_f32 v[60:61], v[94:95], v[220:221]
	v_pk_mul_f32 v[62:63], v[88:89], v[220:221]
	v_pk_fma_f32 v[60:61], v[92:93], v[222:223], v[60:61]
	v_pk_fma_f32 v[62:63], v[90:91], v[222:223], v[62:63]
	v_add_f32_e32 v60, v60, v61
	v_add_f32_e32 v62, v62, v63
	v_pk_mul_f32 v[94:95], v[94:95], v[216:217]
	v_pk_mul_f32 v[92:93], v[92:93], v[218:219]
	v_add_f32_dpp v60, v60, v60 quad_perm:[1,0,3,2] row_mask:0xf bank_mask:0xf bound_ctrl:1
	v_add_f32_dpp v62, v62, v62 quad_perm:[1,0,3,2] row_mask:0xf bank_mask:0xf bound_ctrl:1
	v_pk_fma_f32 v[94:95], v[236:237], v[228:229], v[94:95] op_sel_hi:[0,1,1]
	v_add_f32_dpp v60, v60, v60 quad_perm:[2,3,0,1] row_mask:0xf bank_mask:0xf bound_ctrl:1
	v_add_f32_dpp v62, v62, v62 quad_perm:[2,3,0,1] row_mask:0xf bank_mask:0xf bound_ctrl:1
	v_pk_fma_f32 v[92:93], v[236:237], v[230:231], v[92:93] op_sel_hi:[0,1,1]
	v_add_f32_dpp v60, v60, v60 row_half_mirror row_mask:0xf bank_mask:0xf bound_ctrl:1
	v_add_f32_dpp v62, v62, v62 row_half_mirror row_mask:0xf bank_mask:0xf bound_ctrl:1
	ds_read_b128 v[220:223], v74 offset:31744
	v_add_f32_dpp v60, v60, v60 row_mirror row_mask:0xf bank_mask:0xf bound_ctrl:1
	v_add_f32_dpp v62, v62, v62 row_mirror row_mask:0xf bank_mask:0xf bound_ctrl:1
	ds_read_b128 v[228:231], v74 offset:32256
	ds_read_b32 v236, v75 offset:32768
	v_pk_fma_f32 v[94:95], v[224:225], v[60:61], v[94:95] op_sel_hi:[1,0,1] neg_lo:[1,0,0] neg_hi:[1,0,0]
	v_pk_fma_f32 v[92:93], v[226:227], v[60:61], v[92:93] op_sel_hi:[1,0,1] neg_lo:[1,0,0] neg_hi:[1,0,0]
	v_pk_mul_f32 v[238:239], v[224:225], v[62:63] op_sel_hi:[1,0]
	v_pk_mul_f32 v[240:241], v[226:227], v[62:63] op_sel_hi:[1,0]
	ds_read_b128 v[224:227], v74 offset:32000
	v_pk_mul_f32 v[64:65], v[232:233], v[94:95]
	v_pk_fma_f32 v[88:89], v[88:89], v[216:217], v[238:239] neg_lo:[0,0,1] neg_hi:[0,0,1]
	v_pk_fma_f32 v[90:91], v[90:91], v[218:219], v[240:241] neg_lo:[0,0,1] neg_hi:[0,0,1]
	ds_read_b128 v[216:219], v74 offset:31488
	v_pk_fma_f32 v[64:65], v[234:235], v[92:93], v[64:65]
	v_pk_mul_f32 v[66:67], v[232:233], v[88:89]
	v_pk_fma_f32 v[66:67], v[234:235], v[90:91], v[66:67]
	ds_read_b128 v[232:235], v74 offset:32512
	v_add_f32_e32 v146, v64, v65
	v_add_f32_e32 v167, v66, v67
	s_waitcnt lgkmcnt(6)
	v_pk_mul_f32 v[60:61], v[94:95], v[126:127]
	v_pk_mul_f32 v[62:63], v[88:89], v[126:127]
	v_pk_fma_f32 v[60:61], v[92:93], v[128:129], v[60:61]
	v_pk_fma_f32 v[62:63], v[90:91], v[128:129], v[62:63]
	v_add_f32_e32 v60, v60, v61
	v_add_f32_e32 v62, v62, v63
	v_pk_mul_f32 v[94:95], v[94:95], v[122:123]
	v_pk_mul_f32 v[92:93], v[92:93], v[124:125]
	v_add_f32_dpp v60, v60, v60 quad_perm:[1,0,3,2] row_mask:0xf bank_mask:0xf bound_ctrl:1
	v_add_f32_dpp v62, v62, v62 quad_perm:[1,0,3,2] row_mask:0xf bank_mask:0xf bound_ctrl:1
	v_pk_fma_f32 v[94:95], v[142:143], v[134:135], v[94:95] op_sel_hi:[0,1,1]
	v_add_f32_dpp v60, v60, v60 quad_perm:[2,3,0,1] row_mask:0xf bank_mask:0xf bound_ctrl:1
	v_add_f32_dpp v62, v62, v62 quad_perm:[2,3,0,1] row_mask:0xf bank_mask:0xf bound_ctrl:1
	v_pk_fma_f32 v[92:93], v[142:143], v[136:137], v[92:93] op_sel_hi:[0,1,1]
	v_add_f32_dpp v60, v60, v60 row_half_mirror row_mask:0xf bank_mask:0xf bound_ctrl:1
	v_add_f32_dpp v62, v62, v62 row_half_mirror row_mask:0xf bank_mask:0xf bound_ctrl:1
	ds_read_b128 v[126:129], v74 offset:33280
	v_add_f32_dpp v60, v60, v60 row_mirror row_mask:0xf bank_mask:0xf bound_ctrl:1
	v_add_f32_dpp v62, v62, v62 row_mirror row_mask:0xf bank_mask:0xf bound_ctrl:1
	ds_read_b128 v[134:137], v74 offset:33792
	ds_read_b32 v142, v75 offset:34304
	v_pk_fma_f32 v[94:95], v[130:131], v[60:61], v[94:95] op_sel_hi:[1,0,1] neg_lo:[1,0,0] neg_hi:[1,0,0]
	v_pk_fma_f32 v[92:93], v[132:133], v[60:61], v[92:93] op_sel_hi:[1,0,1] neg_lo:[1,0,0] neg_hi:[1,0,0]
	v_pk_mul_f32 v[238:239], v[130:131], v[62:63] op_sel_hi:[1,0]
	v_pk_mul_f32 v[240:241], v[132:133], v[62:63] op_sel_hi:[1,0]
	ds_read_b128 v[130:133], v74 offset:33536
	v_pk_mul_f32 v[64:65], v[138:139], v[94:95]
	v_pk_fma_f32 v[88:89], v[88:89], v[122:123], v[238:239] neg_lo:[0,0,1] neg_hi:[0,0,1]
	v_pk_fma_f32 v[90:91], v[90:91], v[124:125], v[240:241] neg_lo:[0,0,1] neg_hi:[0,0,1]
	ds_read_b128 v[122:125], v74 offset:33024
	v_pk_fma_f32 v[64:65], v[140:141], v[92:93], v[64:65]
	v_pk_mul_f32 v[66:67], v[138:139], v[88:89]
	v_pk_fma_f32 v[66:67], v[140:141], v[90:91], v[66:67]
	ds_read_b128 v[138:141], v74 offset:34048
	v_add_f32_e32 v147, v64, v65
	v_add_f32_e32 v168, v66, v67
	s_waitcnt lgkmcnt(6)
	v_pk_mul_f32 v[60:61], v[94:95], v[220:221]
	v_pk_mul_f32 v[62:63], v[88:89], v[220:221]
	v_pk_fma_f32 v[60:61], v[92:93], v[222:223], v[60:61]
	v_pk_fma_f32 v[62:63], v[90:91], v[222:223], v[62:63]
	v_add_f32_e32 v60, v60, v61
	v_add_f32_e32 v62, v62, v63
	v_pk_mul_f32 v[94:95], v[94:95], v[216:217]
	v_pk_mul_f32 v[92:93], v[92:93], v[218:219]
	v_add_f32_dpp v60, v60, v60 quad_perm:[1,0,3,2] row_mask:0xf bank_mask:0xf bound_ctrl:1
	v_add_f32_dpp v62, v62, v62 quad_perm:[1,0,3,2] row_mask:0xf bank_mask:0xf bound_ctrl:1
	v_pk_fma_f32 v[94:95], v[236:237], v[228:229], v[94:95] op_sel_hi:[0,1,1]
	v_add_f32_dpp v60, v60, v60 quad_perm:[2,3,0,1] row_mask:0xf bank_mask:0xf bound_ctrl:1
	v_add_f32_dpp v62, v62, v62 quad_perm:[2,3,0,1] row_mask:0xf bank_mask:0xf bound_ctrl:1
	v_pk_fma_f32 v[92:93], v[236:237], v[230:231], v[92:93] op_sel_hi:[0,1,1]
	v_add_f32_dpp v60, v60, v60 row_half_mirror row_mask:0xf bank_mask:0xf bound_ctrl:1
	v_add_f32_dpp v62, v62, v62 row_half_mirror row_mask:0xf bank_mask:0xf bound_ctrl:1
	ds_read_b128 v[220:223], v74 offset:34816
	v_add_f32_dpp v60, v60, v60 row_mirror row_mask:0xf bank_mask:0xf bound_ctrl:1
	v_add_f32_dpp v62, v62, v62 row_mirror row_mask:0xf bank_mask:0xf bound_ctrl:1
	ds_read_b128 v[228:231], v74 offset:35328
	ds_read_b32 v236, v75 offset:35840
	v_pk_fma_f32 v[94:95], v[224:225], v[60:61], v[94:95] op_sel_hi:[1,0,1] neg_lo:[1,0,0] neg_hi:[1,0,0]
	v_pk_fma_f32 v[92:93], v[226:227], v[60:61], v[92:93] op_sel_hi:[1,0,1] neg_lo:[1,0,0] neg_hi:[1,0,0]
	v_pk_mul_f32 v[238:239], v[224:225], v[62:63] op_sel_hi:[1,0]
	v_pk_mul_f32 v[240:241], v[226:227], v[62:63] op_sel_hi:[1,0]
	ds_read_b128 v[224:227], v74 offset:35072
	v_pk_mul_f32 v[64:65], v[232:233], v[94:95]
	v_pk_fma_f32 v[88:89], v[88:89], v[216:217], v[238:239] neg_lo:[0,0,1] neg_hi:[0,0,1]
	v_pk_fma_f32 v[90:91], v[90:91], v[218:219], v[240:241] neg_lo:[0,0,1] neg_hi:[0,0,1]
	ds_read_b128 v[216:219], v74 offset:34560
	v_pk_fma_f32 v[64:65], v[234:235], v[92:93], v[64:65]
	v_pk_mul_f32 v[66:67], v[232:233], v[88:89]
	v_pk_fma_f32 v[66:67], v[234:235], v[90:91], v[66:67]
	ds_read_b128 v[232:235], v74 offset:35584
	v_add_f32_e32 v148, v64, v65
	v_add_f32_e32 v169, v66, v67
	s_waitcnt lgkmcnt(6)
; template <bool DUAL>
; __device__ __forceinline__ void rwkv_tile(const Params& p, int l, int tile, unsigned char* smem) {
;     ...
;       for (int i = 0; i < 32; ++i) {
;         const int inx = (i + 1) & 31;
;         const float4 nw4 = *(const float4*)(rp + inx * 384), nkk4 = *(const float4*)(rp + inx * 384 + 64), nkb4 = *(const float4*)(rp + inx * 384 + 128);
;         const float4 nkd4 = *(const float4*)(rp + inx * 384 + 192), nr4 = *(const float4*)(rp + inx * 384 + 256);
;         const float nv = vp[inx * 384];
;         v2f t = sA * (v2f){kk4.x, kk4.y};
;         t = sB * (v2f){kk4.z, kk4.w} + t;
;         float sa = t.x + t.y, ia = 0.f;
;         if (DUAL) {
;           v2f ti = iA * (v2f){kk4.x, kk4.y};
;           ti = iB * (v2f){kk4.z, kk4.w} + ti;
;           ia = ti.x + ti.y;
;           sa += dppf<0xB1>(sa); ia += dppf<0xB1>(ia);
;           sa += dppf<0x4E>(sa); ia += dppf<0x4E>(ia);
;           sa += dppf<0x141>(sa); ia += dppf<0x141>(ia);
;           sa += dppf<0x140>(sa); ia += dppf<0x140>(ia);
;         } else {
;           sa = sum16(sa);
;         }
;         v2f cA = sA * (v2f){w4.x, w4.y} + (v2f){kd4.x, kd4.y} * v;
;         v2f cB = sB * (v2f){w4.z, w4.w} + (v2f){kd4.z, kd4.w} * v;
;         sA = cA - (v2f){kb4.x, kb4.y} * sa;
;         sB = cB - (v2f){kb4.z, kb4.w} * sa;
;         v2f u = sA * (v2f){r4.x, r4.y};
;         u = sB * (v2f){r4.z, r4.w} + u;
;         float y = u.x + u.y, g = 0.f;
;         if (DUAL) {
;           iA = iA * (v2f){w4.x, w4.y} - (v2f){kb4.x, kb4.y} * ia;
;           iB = iB * (v2f){w4.z, w4.w} - (v2f){kb4.z, kb4.w} * ia;
;           v2f ui = iA * (v2f){r4.x, r4.y};
;           ui = iB * (v2f){r4.z, r4.w} + ui;
;           g = ui.x + ui.y;
;           y += dppf<0xB1>(y); g += dppf<0xB1>(g);
;           y += dppf<0x4E>(y); g += dppf<0x4E>(g);
;           y += dppf<0x141>(y); g += dppf<0x141>(g);
;           y += dppf<0x140>(y); g += dppf<0x140>(g);
	v_pk_mul_f32 v[60:61], v[94:95], v[126:127]
	v_pk_mul_f32 v[62:63], v[88:89], v[126:127]
	v_pk_fma_f32 v[60:61], v[92:93], v[128:129], v[60:61]
	v_pk_fma_f32 v[62:63], v[90:91], v[128:129], v[62:63]
	v_add_f32_e32 v60, v60, v61
	v_add_f32_e32 v62, v62, v63
	v_pk_mul_f32 v[94:95], v[94:95], v[122:123]
	v_pk_mul_f32 v[92:93], v[92:93], v[124:125]
	v_add_f32_dpp v60, v60, v60 quad_perm:[1,0,3,2] row_mask:0xf bank_mask:0xf bound_ctrl:1
	v_add_f32_dpp v62, v62, v62 quad_perm:[1,0,3,2] row_mask:0xf bank_mask:0xf bound_ctrl:1
	v_pk_fma_f32 v[94:95], v[142:143], v[134:135], v[94:95] op_sel_hi:[0,1,1]
	v_add_f32_dpp v60, v60, v60 quad_perm:[2,3,0,1] row_mask:0xf bank_mask:0xf bound_ctrl:1
	v_add_f32_dpp v62, v62, v62 quad_perm:[2,3,0,1] row_mask:0xf bank_mask:0xf bound_ctrl:1
	v_pk_fma_f32 v[92:93], v[142:143], v[136:137], v[92:93] op_sel_hi:[0,1,1]
	v_add_f32_dpp v60, v60, v60 row_half_mirror row_mask:0xf bank_mask:0xf bound_ctrl:1
	v_add_f32_dpp v62, v62, v62 row_half_mirror row_mask:0xf bank_mask:0xf bound_ctrl:1
	ds_read_b128 v[126:129], v74 offset:36352
	v_add_f32_dpp v60, v60, v60 row_mirror row_mask:0xf bank_mask:0xf bound_ctrl:1
	v_add_f32_dpp v62, v62, v62 row_mirror row_mask:0xf bank_mask:0xf bound_ctrl:1
	ds_read_b128 v[134:137], v74 offset:36864
	ds_read_b32 v142, v75 offset:37376
	v_pk_fma_f32 v[94:95], v[130:131], v[60:61], v[94:95] op_sel_hi:[1,0,1] neg_lo:[1,0,0] neg_hi:[1,0,0]
	v_pk_fma_f32 v[92:93], v[132:133], v[60:61], v[92:93] op_sel_hi:[1,0,1] neg_lo:[1,0,0] neg_hi:[1,0,0]
	v_pk_mul_f32 v[238:239], v[130:131], v[62:63] op_sel_hi:[1,0]
	v_pk_mul_f32 v[240:241], v[132:133], v[62:63] op_sel_hi:[1,0]
	ds_read_b128 v[130:133], v74 offset:36608
	v_pk_mul_f32 v[64:65], v[138:139], v[94:95]
	v_pk_fma_f32 v[88:89], v[88:89], v[122:123], v[238:239] neg_lo:[0,0,1] neg_hi:[0,0,1]
	v_pk_fma_f32 v[90:91], v[90:91], v[124:125], v[240:241] neg_lo:[0,0,1] neg_hi:[0,0,1]
	ds_read_b128 v[122:125], v74 offset:36096
	v_pk_fma_f32 v[64:65], v[140:141], v[92:93], v[64:65]
	v_pk_mul_f32 v[66:67], v[138:139], v[88:89]
	v_pk_fma_f32 v[66:67], v[140:141], v[90:91], v[66:67]
	ds_read_b128 v[138:141], v74 offset:37120
	v_add_f32_e32 v149, v64, v65
	v_add_f32_e32 v170, v66, v67
	s_waitcnt lgkmcnt(6)
	v_pk_mul_f32 v[60:61], v[94:95], v[220:221]
	v_pk_mul_f32 v[62:63], v[88:89], v[220:221]
	v_pk_fma_f32 v[60:61], v[92:93], v[222:223], v[60:61]
	v_pk_fma_f32 v[62:63], v[90:91], v[222:223], v[62:63]
	v_add_f32_e32 v60, v60, v61
	v_add_f32_e32 v62, v62, v63
	v_pk_mul_f32 v[94:95], v[94:95], v[216:217]
	v_pk_mul_f32 v[92:93], v[92:93], v[218:219]
	v_add_f32_dpp v60, v60, v60 quad_perm:[1,0,3,2] row_mask:0xf bank_mask:0xf bound_ctrl:1
	v_add_f32_dpp v62, v62, v62 quad_perm:[1,0,3,2] row_mask:0xf bank_mask:0xf bound_ctrl:1
	v_pk_fma_f32 v[94:95], v[236:237], v[228:229], v[94:95] op_sel_hi:[0,1,1]
	v_add_f32_dpp v60, v60, v60 quad_perm:[2,3,0,1] row_mask:0xf bank_mask:0xf bound_ctrl:1
	v_add_f32_dpp v62, v62, v62 quad_perm:[2,3,0,1] row_mask:0xf bank_mask:0xf bound_ctrl:1
	v_pk_fma_f32 v[92:93], v[236:237], v[230:231], v[92:93] op_sel_hi:[0,1,1]
	v_add_f32_dpp v60, v60, v60 row_half_mirror row_mask:0xf bank_mask:0xf bound_ctrl:1
	v_add_f32_dpp v62, v62, v62 row_half_mirror row_mask:0xf bank_mask:0xf bound_ctrl:1
	ds_read_b128 v[220:223], v74 offset:37888
	v_add_f32_dpp v60, v60, v60 row_mirror row_mask:0xf bank_mask:0xf bound_ctrl:1
	v_add_f32_dpp v62, v62, v62 row_mirror row_mask:0xf bank_mask:0xf bound_ctrl:1
	ds_read_b128 v[228:231], v74 offset:38400
	ds_read_b32 v236, v75 offset:38912
	v_pk_fma_f32 v[94:95], v[224:225], v[60:61], v[94:95] op_sel_hi:[1,0,1] neg_lo:[1,0,0] neg_hi:[1,0,0]
	v_pk_fma_f32 v[92:93], v[226:227], v[60:61], v[92:93] op_sel_hi:[1,0,1] neg_lo:[1,0,0] neg_hi:[1,0,0]
	v_pk_mul_f32 v[238:239], v[224:225], v[62:63] op_sel_hi:[1,0]
	v_pk_mul_f32 v[240:241], v[226:227], v[62:63] op_sel_hi:[1,0]
	ds_read_b128 v[224:227], v74 offset:38144
	v_pk_mul_f32 v[64:65], v[232:233], v[94:95]
	v_pk_fma_f32 v[88:89], v[88:89], v[216:217], v[238:239] neg_lo:[0,0,1] neg_hi:[0,0,1]
	v_pk_fma_f32 v[90:91], v[90:91], v[218:219], v[240:241] neg_lo:[0,0,1] neg_hi:[0,0,1]
	ds_read_b128 v[216:219], v74 offset:37632
	v_pk_fma_f32 v[64:65], v[234:235], v[92:93], v[64:65]
	v_pk_mul_f32 v[66:67], v[232:233], v[88:89]
	v_pk_fma_f32 v[66:67], v[234:235], v[90:91], v[66:67]
	ds_read_b128 v[232:235], v74 offset:38656
	v_add_f32_e32 v150, v64, v65
	v_add_f32_e32 v171, v66, v67
	s_waitcnt lgkmcnt(6)
	v_pk_mul_f32 v[60:61], v[94:95], v[126:127]
	v_pk_mul_f32 v[62:63], v[88:89], v[126:127]
	v_pk_fma_f32 v[60:61], v[92:93], v[128:129], v[60:61]
	v_pk_fma_f32 v[62:63], v[90:91], v[128:129], v[62:63]
	v_add_f32_e32 v60, v60, v61
	v_add_f32_e32 v62, v62, v63
	v_pk_mul_f32 v[94:95], v[94:95], v[122:123]
	v_pk_mul_f32 v[92:93], v[92:93], v[124:125]
	v_add_f32_dpp v60, v60, v60 quad_perm:[1,0,3,2] row_mask:0xf bank_mask:0xf bound_ctrl:1
	v_add_f32_dpp v62, v62, v62 quad_perm:[1,0,3,2] row_mask:0xf bank_mask:0xf bound_ctrl:1
	v_pk_fma_f32 v[94:95], v[142:143], v[134:135], v[94:95] op_sel_hi:[0,1,1]
	v_add_f32_dpp v60, v60, v60 quad_perm:[2,3,0,1] row_mask:0xf bank_mask:0xf bound_ctrl:1
	v_add_f32_dpp v62, v62, v62 quad_perm:[2,3,0,1] row_mask:0xf bank_mask:0xf bound_ctrl:1
	v_pk_fma_f32 v[92:93], v[142:143], v[136:137], v[92:93] op_sel_hi:[0,1,1]
	v_add_f32_dpp v60, v60, v60 row_half_mirror row_mask:0xf bank_mask:0xf bound_ctrl:1
	v_add_f32_dpp v62, v62, v62 row_half_mirror row_mask:0xf bank_mask:0xf bound_ctrl:1
	ds_read_b128 v[126:129], v74 offset:39424
	v_add_f32_dpp v60, v60, v60 row_mirror row_mask:0xf bank_mask:0xf bound_ctrl:1
	v_add_f32_dpp v62, v62, v62 row_mirror row_mask:0xf bank_mask:0xf bound_ctrl:1
	ds_read_b128 v[134:137], v74 offset:39936
	ds_read_b32 v142, v75 offset:40448
	v_pk_fma_f32 v[94:95], v[130:131], v[60:61], v[94:95] op_sel_hi:[1,0,1] neg_lo:[1,0,0] neg_hi:[1,0,0]
	v_pk_fma_f32 v[92:93], v[132:133], v[60:61], v[92:93] op_sel_hi:[1,0,1] neg_lo:[1,0,0] neg_hi:[1,0,0]
	v_pk_mul_f32 v[238:239], v[130:131], v[62:63] op_sel_hi:[1,0]
	v_pk_mul_f32 v[240:241], v[132:133], v[62:63] op_sel_hi:[1,0]
	ds_read_b128 v[130:133], v74 offset:39680
	v_pk_mul_f32 v[64:65], v[138:139], v[94:95]
	v_pk_fma_f32 v[88:89], v[88:89], v[122:123], v[238:239] neg_lo:[0,0,1] neg_hi:[0,0,1]
	v_pk_fma_f32 v[90:91], v[90:91], v[124:125], v[240:241] neg_lo:[0,0,1] neg_hi:[0,0,1]
	ds_read_b128 v[122:125], v74 offset:39168
	v_pk_fma_f32 v[64:65], v[140:141], v[92:93], v[64:65]
	v_pk_mul_f32 v[66:67], v[138:139], v[88:89]
	v_pk_fma_f32 v[66:67], v[140:141], v[90:91], v[66:67]
	ds_read_b128 v[138:141], v74 offset:40192
	v_add_f32_e32 v151, v64, v65
	v_add_f32_e32 v172, v66, v67
	s_waitcnt lgkmcnt(6)
; template <bool DUAL>
; __device__ __forceinline__ void rwkv_tile(const Params& p, int l, int tile, unsigned char* smem) {
;     ...
;       for (int i = 0; i < 32; ++i) {
;         const int inx = (i + 1) & 31;
;         const float4 nw4 = *(const float4*)(rp + inx * 384), nkk4 = *(const float4*)(rp + inx * 384 + 64), nkb4 = *(const float4*)(rp + inx * 384 + 128);
;         const float4 nkd4 = *(const float4*)(rp + inx * 384 + 192), nr4 = *(const float4*)(rp + inx * 384 + 256);
;         const float nv = vp[inx * 384];
;         v2f t = sA * (v2f){kk4.x, kk4.y};
;         t = sB * (v2f){kk4.z, kk4.w} + t;
;         float sa = t.x + t.y, ia = 0.f;
;         if (DUAL) {
;           v2f ti = iA * (v2f){kk4.x, kk4.y};
;           ti = iB * (v2f){kk4.z, kk4.w} + ti;
;           ia = ti.x + ti.y;
;           sa += dppf<0xB1>(sa); ia += dppf<0xB1>(ia);
;           sa += dppf<0x4E>(sa); ia += dppf<0x4E>(ia);
;           sa += dppf<0x141>(sa); ia += dppf<0x141>(ia);
;           sa += dppf<0x140>(sa); ia += dppf<0x140>(ia);
;         } else {
;           sa = sum16(sa);
;         }
;         v2f cA = sA * (v2f){w4.x, w4.y} + (v2f){kd4.x, kd4.y} * v;
;         v2f cB = sB * (v2f){w4.z, w4.w} + (v2f){kd4.z, kd4.w} * v;
;         sA = cA - (v2f){kb4.x, kb4.y} * sa;
;         sB = cB - (v2f){kb4.z, kb4.w} * sa;
;         v2f u = sA * (v2f){r4.x, r4.y};
;         u = sB * (v2f){r4.z, r4.w} + u;
;         float y = u.x + u.y, g = 0.f;
;         if (DUAL) {
;           iA = iA * (v2f){w4.x, w4.y} - (v2f){kb4.x, kb4.y} * ia;
;           iB = iB * (v2f){w4.z, w4.w} - (v2f){kb4.z, kb4.w} * ia;
;           v2f ui = iA * (v2f){r4.x, r4.y};
;           ui = iB * (v2f){r4.z, r4.w} + ui;
;           g = ui.x + ui.y;
;           y += dppf<0xB1>(y); g += dppf<0xB1>(g);
;           y += dppf<0x4E>(y); g += dppf<0x4E>(g);
;           y += dppf<0x141>(y); g += dppf<0x141>(g);
;           y += dppf<0x140>(y); g += dppf<0x140>(g);
	v_pk_mul_f32 v[60:61], v[94:95], v[220:221]
	v_pk_mul_f32 v[62:63], v[88:89], v[220:221]
	v_pk_fma_f32 v[60:61], v[92:93], v[222:223], v[60:61]
	v_pk_fma_f32 v[62:63], v[90:91], v[222:223], v[62:63]
	v_add_f32_e32 v60, v60, v61
	v_add_f32_e32 v62, v62, v63
	v_pk_mul_f32 v[94:95], v[94:95], v[216:217]
	v_pk_mul_f32 v[92:93], v[92:93], v[218:219]
	v_add_f32_dpp v60, v60, v60 quad_perm:[1,0,3,2] row_mask:0xf bank_mask:0xf bound_ctrl:1
	v_add_f32_dpp v62, v62, v62 quad_perm:[1,0,3,2] row_mask:0xf bank_mask:0xf bound_ctrl:1
	v_pk_fma_f32 v[94:95], v[236:237], v[228:229], v[94:95] op_sel_hi:[0,1,1]
	v_add_f32_dpp v60, v60, v60 quad_perm:[2,3,0,1] row_mask:0xf bank_mask:0xf bound_ctrl:1
	v_add_f32_dpp v62, v62, v62 quad_perm:[2,3,0,1] row_mask:0xf bank_mask:0xf bound_ctrl:1
	v_pk_fma_f32 v[92:93], v[236:237], v[230:231], v[92:93] op_sel_hi:[0,1,1]
	v_add_f32_dpp v60, v60, v60 row_half_mirror row_mask:0xf bank_mask:0xf bound_ctrl:1
	v_add_f32_dpp v62, v62, v62 row_half_mirror row_mask:0xf bank_mask:0xf bound_ctrl:1
	ds_read_b128 v[220:223], v74 offset:40960
	v_add_f32_dpp v60, v60, v60 row_mirror row_mask:0xf bank_mask:0xf bound_ctrl:1
	v_add_f32_dpp v62, v62, v62 row_mirror row_mask:0xf bank_mask:0xf bound_ctrl:1
	ds_read_b128 v[228:231], v74 offset:41472
	ds_read_b32 v236, v75 offset:41984
	v_pk_fma_f32 v[94:95], v[224:225], v[60:61], v[94:95] op_sel_hi:[1,0,1] neg_lo:[1,0,0] neg_hi:[1,0,0]
	v_pk_fma_f32 v[92:93], v[226:227], v[60:61], v[92:93] op_sel_hi:[1,0,1] neg_lo:[1,0,0] neg_hi:[1,0,0]
	v_pk_mul_f32 v[238:239], v[224:225], v[62:63] op_sel_hi:[1,0]
	v_pk_mul_f32 v[240:241], v[226:227], v[62:63] op_sel_hi:[1,0]
	ds_read_b128 v[224:227], v74 offset:41216
	v_pk_mul_f32 v[64:65], v[232:233], v[94:95]
	v_pk_fma_f32 v[88:89], v[88:89], v[216:217], v[238:239] neg_lo:[0,0,1] neg_hi:[0,0,1]
	v_pk_fma_f32 v[90:91], v[90:91], v[218:219], v[240:241] neg_lo:[0,0,1] neg_hi:[0,0,1]
	ds_read_b128 v[216:219], v74 offset:40704
	v_pk_fma_f32 v[64:65], v[234:235], v[92:93], v[64:65]
	v_pk_mul_f32 v[66:67], v[232:233], v[88:89]
	v_pk_fma_f32 v[66:67], v[234:235], v[90:91], v[66:67]
	ds_read_b128 v[232:235], v74 offset:41728
	v_add_f32_e32 v152, v64, v65
	v_add_f32_e32 v173, v66, v67
	s_waitcnt lgkmcnt(6)
	v_pk_mul_f32 v[60:61], v[94:95], v[126:127]
	v_pk_mul_f32 v[62:63], v[88:89], v[126:127]
	v_pk_fma_f32 v[60:61], v[92:93], v[128:129], v[60:61]
	v_pk_fma_f32 v[62:63], v[90:91], v[128:129], v[62:63]
	v_add_f32_e32 v60, v60, v61
	v_add_f32_e32 v62, v62, v63
	v_pk_mul_f32 v[94:95], v[94:95], v[122:123]
	v_pk_mul_f32 v[92:93], v[92:93], v[124:125]
	v_add_f32_dpp v60, v60, v60 quad_perm:[1,0,3,2] row_mask:0xf bank_mask:0xf bound_ctrl:1
	v_add_f32_dpp v62, v62, v62 quad_perm:[1,0,3,2] row_mask:0xf bank_mask:0xf bound_ctrl:1
	v_pk_fma_f32 v[94:95], v[142:143], v[134:135], v[94:95] op_sel_hi:[0,1,1]
	v_add_f32_dpp v60, v60, v60 quad_perm:[2,3,0,1] row_mask:0xf bank_mask:0xf bound_ctrl:1
	v_add_f32_dpp v62, v62, v62 quad_perm:[2,3,0,1] row_mask:0xf bank_mask:0xf bound_ctrl:1
	v_pk_fma_f32 v[92:93], v[142:143], v[136:137], v[92:93] op_sel_hi:[0,1,1]
	v_add_f32_dpp v60, v60, v60 row_half_mirror row_mask:0xf bank_mask:0xf bound_ctrl:1
	v_add_f32_dpp v62, v62, v62 row_half_mirror row_mask:0xf bank_mask:0xf bound_ctrl:1
	ds_read_b128 v[126:129], v74 offset:42496
	v_add_f32_dpp v60, v60, v60 row_mirror row_mask:0xf bank_mask:0xf bound_ctrl:1
	v_add_f32_dpp v62, v62, v62 row_mirror row_mask:0xf bank_mask:0xf bound_ctrl:1
	ds_read_b128 v[134:137], v74 offset:43008
	ds_read_b32 v142, v75 offset:43520
	v_pk_fma_f32 v[94:95], v[130:131], v[60:61], v[94:95] op_sel_hi:[1,0,1] neg_lo:[1,0,0] neg_hi:[1,0,0]
	v_pk_fma_f32 v[92:93], v[132:133], v[60:61], v[92:93] op_sel_hi:[1,0,1] neg_lo:[1,0,0] neg_hi:[1,0,0]
	v_pk_mul_f32 v[238:239], v[130:131], v[62:63] op_sel_hi:[1,0]
	v_pk_mul_f32 v[240:241], v[132:133], v[62:63] op_sel_hi:[1,0]
	ds_read_b128 v[130:133], v74 offset:42752
	v_pk_mul_f32 v[64:65], v[138:139], v[94:95]
	v_pk_fma_f32 v[88:89], v[88:89], v[122:123], v[238:239] neg_lo:[0,0,1] neg_hi:[0,0,1]
	v_pk_fma_f32 v[90:91], v[90:91], v[124:125], v[240:241] neg_lo:[0,0,1] neg_hi:[0,0,1]
	ds_read_b128 v[122:125], v74 offset:42240
	v_pk_fma_f32 v[64:65], v[140:141], v[92:93], v[64:65]
	v_pk_mul_f32 v[66:67], v[138:139], v[88:89]
	v_pk_fma_f32 v[66:67], v[140:141], v[90:91], v[66:67]
	ds_read_b128 v[138:141], v74 offset:43264
	v_add_f32_e32 v153, v64, v65
	v_add_f32_e32 v174, v66, v67
	s_waitcnt lgkmcnt(6)
	v_pk_mul_f32 v[60:61], v[94:95], v[220:221]
	v_pk_mul_f32 v[62:63], v[88:89], v[220:221]
	v_pk_fma_f32 v[60:61], v[92:93], v[222:223], v[60:61]
	v_pk_fma_f32 v[62:63], v[90:91], v[222:223], v[62:63]
	v_add_f32_e32 v60, v60, v61
	v_add_f32_e32 v62, v62, v63
	v_pk_mul_f32 v[94:95], v[94:95], v[216:217]
	v_pk_mul_f32 v[92:93], v[92:93], v[218:219]
	v_add_f32_dpp v60, v60, v60 quad_perm:[1,0,3,2] row_mask:0xf bank_mask:0xf bound_ctrl:1
	v_add_f32_dpp v62, v62, v62 quad_perm:[1,0,3,2] row_mask:0xf bank_mask:0xf bound_ctrl:1
	v_pk_fma_f32 v[94:95], v[236:237], v[228:229], v[94:95] op_sel_hi:[0,1,1]
	v_add_f32_dpp v60, v60, v60 quad_perm:[2,3,0,1] row_mask:0xf bank_mask:0xf bound_ctrl:1
	v_add_f32_dpp v62, v62, v62 quad_perm:[2,3,0,1] row_mask:0xf bank_mask:0xf bound_ctrl:1
	v_pk_fma_f32 v[92:93], v[236:237], v[230:231], v[92:93] op_sel_hi:[0,1,1]
	v_add_f32_dpp v60, v60, v60 row_half_mirror row_mask:0xf bank_mask:0xf bound_ctrl:1
	v_add_f32_dpp v62, v62, v62 row_half_mirror row_mask:0xf bank_mask:0xf bound_ctrl:1
	ds_read_b128 v[220:223], v74 offset:44032
	v_add_f32_dpp v60, v60, v60 row_mirror row_mask:0xf bank_mask:0xf bound_ctrl:1
	v_add_f32_dpp v62, v62, v62 row_mirror row_mask:0xf bank_mask:0xf bound_ctrl:1
	ds_read_b128 v[228:231], v74 offset:44544
	ds_read_b32 v236, v75 offset:45056
	v_pk_fma_f32 v[94:95], v[224:225], v[60:61], v[94:95] op_sel_hi:[1,0,1] neg_lo:[1,0,0] neg_hi:[1,0,0]
	v_pk_fma_f32 v[92:93], v[226:227], v[60:61], v[92:93] op_sel_hi:[1,0,1] neg_lo:[1,0,0] neg_hi:[1,0,0]
	v_pk_mul_f32 v[238:239], v[224:225], v[62:63] op_sel_hi:[1,0]
	v_pk_mul_f32 v[240:241], v[226:227], v[62:63] op_sel_hi:[1,0]
	ds_read_b128 v[224:227], v74 offset:44288
	v_pk_mul_f32 v[64:65], v[232:233], v[94:95]
	v_pk_fma_f32 v[88:89], v[88:89], v[216:217], v[238:239] neg_lo:[0,0,1] neg_hi:[0,0,1]
	v_pk_fma_f32 v[90:91], v[90:91], v[218:219], v[240:241] neg_lo:[0,0,1] neg_hi:[0,0,1]
	ds_read_b128 v[216:219], v74 offset:43776
	v_pk_fma_f32 v[64:65], v[234:235], v[92:93], v[64:65]
	v_pk_mul_f32 v[66:67], v[232:233], v[88:89]
	v_pk_fma_f32 v[66:67], v[234:235], v[90:91], v[66:67]
	ds_read_b128 v[232:235], v74 offset:44800
	v_add_f32_e32 v154, v64, v65
	v_add_f32_e32 v175, v66, v67
	s_waitcnt lgkmcnt(6)
; template <bool DUAL>
; __device__ __forceinline__ void rwkv_tile(const Params& p, int l, int tile, unsigned char* smem) {
;     ...
;       for (int i = 0; i < 32; ++i) {
;         const int inx = (i + 1) & 31;
;         const float4 nw4 = *(const float4*)(rp + inx * 384), nkk4 = *(const float4*)(rp + inx * 384 + 64), nkb4 = *(const float4*)(rp + inx * 384 + 128);
;         const float4 nkd4 = *(const float4*)(rp + inx * 384 + 192), nr4 = *(const float4*)(rp + inx * 384 + 256);
;         const float nv = vp[inx * 384];
;         v2f t = sA * (v2f){kk4.x, kk4.y};
;         t = sB * (v2f){kk4.z, kk4.w} + t;
;         float sa = t.x + t.y, ia = 0.f;
;         if (DUAL) {
;           v2f ti = iA * (v2f){kk4.x, kk4.y};
;           ti = iB * (v2f){kk4.z, kk4.w} + ti;
;           ia = ti.x + ti.y;
;           sa += dppf<0xB1>(sa); ia += dppf<0xB1>(ia);
;           sa += dppf<0x4E>(sa); ia += dppf<0x4E>(ia);
;           sa += dppf<0x141>(sa); ia += dppf<0x141>(ia);
;           sa += dppf<0x140>(sa); ia += dppf<0x140>(ia);
;         } else {
;           sa = sum16(sa);
;         }
;         v2f cA = sA * (v2f){w4.x, w4.y} + (v2f){kd4.x, kd4.y} * v;
;         v2f cB = sB * (v2f){w4.z, w4.w} + (v2f){kd4.z, kd4.w} * v;
;         sA = cA - (v2f){kb4.x, kb4.y} * sa;
;         sB = cB - (v2f){kb4.z, kb4.w} * sa;
;         v2f u = sA * (v2f){r4.x, r4.y};
;         u = sB * (v2f){r4.z, r4.w} + u;
;         float y = u.x + u.y, g = 0.f;
;         if (DUAL) {
;           iA = iA * (v2f){w4.x, w4.y} - (v2f){kb4.x, kb4.y} * ia;
;           iB = iB * (v2f){w4.z, w4.w} - (v2f){kb4.z, kb4.w} * ia;
;           v2f ui = iA * (v2f){r4.x, r4.y};
;           ui = iB * (v2f){r4.z, r4.w} + ui;
;           g = ui.x + ui.y;
;           y += dppf<0xB1>(y); g += dppf<0xB1>(g);
;           y += dppf<0x4E>(y); g += dppf<0x4E>(g);
;           y += dppf<0x141>(y); g += dppf<0x141>(g);
;           y += dppf<0x140>(y); g += dppf<0x140>(g);
	v_pk_mul_f32 v[60:61], v[94:95], v[126:127]
	v_pk_mul_f32 v[62:63], v[88:89], v[126:127]
	v_pk_fma_f32 v[60:61], v[92:93], v[128:129], v[60:61]
	v_pk_fma_f32 v[62:63], v[90:91], v[128:129], v[62:63]
	v_add_f32_e32 v60, v60, v61
	v_add_f32_e32 v62, v62, v63
	v_pk_mul_f32 v[94:95], v[94:95], v[122:123]
	v_pk_mul_f32 v[92:93], v[92:93], v[124:125]
	v_add_f32_dpp v60, v60, v60 quad_perm:[1,0,3,2] row_mask:0xf bank_mask:0xf bound_ctrl:1
	v_add_f32_dpp v62, v62, v62 quad_perm:[1,0,3,2] row_mask:0xf bank_mask:0xf bound_ctrl:1
	v_pk_fma_f32 v[94:95], v[142:143], v[134:135], v[94:95] op_sel_hi:[0,1,1]
	v_add_f32_dpp v60, v60, v60 quad_perm:[2,3,0,1] row_mask:0xf bank_mask:0xf bound_ctrl:1
	v_add_f32_dpp v62, v62, v62 quad_perm:[2,3,0,1] row_mask:0xf bank_mask:0xf bound_ctrl:1
	v_pk_fma_f32 v[92:93], v[142:143], v[136:137], v[92:93] op_sel_hi:[0,1,1]
	v_add_f32_dpp v60, v60, v60 row_half_mirror row_mask:0xf bank_mask:0xf bound_ctrl:1
	v_add_f32_dpp v62, v62, v62 row_half_mirror row_mask:0xf bank_mask:0xf bound_ctrl:1
	ds_read_b128 v[126:129], v74 offset:45568
	v_add_f32_dpp v60, v60, v60 row_mirror row_mask:0xf bank_mask:0xf bound_ctrl:1
	v_add_f32_dpp v62, v62, v62 row_mirror row_mask:0xf bank_mask:0xf bound_ctrl:1
	ds_read_b128 v[134:137], v74 offset:46080
	ds_read_b32 v142, v75 offset:46592
	v_pk_fma_f32 v[94:95], v[130:131], v[60:61], v[94:95] op_sel_hi:[1,0,1] neg_lo:[1,0,0] neg_hi:[1,0,0]
	v_pk_fma_f32 v[92:93], v[132:133], v[60:61], v[92:93] op_sel_hi:[1,0,1] neg_lo:[1,0,0] neg_hi:[1,0,0]
	v_pk_mul_f32 v[238:239], v[130:131], v[62:63] op_sel_hi:[1,0]
	v_pk_mul_f32 v[240:241], v[132:133], v[62:63] op_sel_hi:[1,0]
	ds_read_b128 v[130:133], v74 offset:45824
	v_pk_mul_f32 v[64:65], v[138:139], v[94:95]
	v_pk_fma_f32 v[88:89], v[88:89], v[122:123], v[238:239] neg_lo:[0,0,1] neg_hi:[0,0,1]
	v_pk_fma_f32 v[90:91], v[90:91], v[124:125], v[240:241] neg_lo:[0,0,1] neg_hi:[0,0,1]
	ds_read_b128 v[122:125], v74 offset:45312
	v_pk_fma_f32 v[64:65], v[140:141], v[92:93], v[64:65]
	v_pk_mul_f32 v[66:67], v[138:139], v[88:89]
	v_pk_fma_f32 v[66:67], v[140:141], v[90:91], v[66:67]
	ds_read_b128 v[138:141], v74 offset:46336
	v_add_f32_e32 v155, v64, v65
	v_add_f32_e32 v176, v66, v67
	s_waitcnt lgkmcnt(6)
	v_pk_mul_f32 v[60:61], v[94:95], v[220:221]
	v_pk_mul_f32 v[62:63], v[88:89], v[220:221]
	v_pk_fma_f32 v[60:61], v[92:93], v[222:223], v[60:61]
	v_pk_fma_f32 v[62:63], v[90:91], v[222:223], v[62:63]
	v_add_f32_e32 v60, v60, v61
	v_add_f32_e32 v62, v62, v63
	v_pk_mul_f32 v[94:95], v[94:95], v[216:217]
	v_pk_mul_f32 v[92:93], v[92:93], v[218:219]
	v_add_f32_dpp v60, v60, v60 quad_perm:[1,0,3,2] row_mask:0xf bank_mask:0xf bound_ctrl:1
	v_add_f32_dpp v62, v62, v62 quad_perm:[1,0,3,2] row_mask:0xf bank_mask:0xf bound_ctrl:1
	v_pk_fma_f32 v[94:95], v[236:237], v[228:229], v[94:95] op_sel_hi:[0,1,1]
	v_add_f32_dpp v60, v60, v60 quad_perm:[2,3,0,1] row_mask:0xf bank_mask:0xf bound_ctrl:1
	v_add_f32_dpp v62, v62, v62 quad_perm:[2,3,0,1] row_mask:0xf bank_mask:0xf bound_ctrl:1
	v_pk_fma_f32 v[92:93], v[236:237], v[230:231], v[92:93] op_sel_hi:[0,1,1]
	v_add_f32_dpp v60, v60, v60 row_half_mirror row_mask:0xf bank_mask:0xf bound_ctrl:1
	v_add_f32_dpp v62, v62, v62 row_half_mirror row_mask:0xf bank_mask:0xf bound_ctrl:1
	ds_read_b128 v[220:223], v74 offset:47104
	v_add_f32_dpp v60, v60, v60 row_mirror row_mask:0xf bank_mask:0xf bound_ctrl:1
	v_add_f32_dpp v62, v62, v62 row_mirror row_mask:0xf bank_mask:0xf bound_ctrl:1
	ds_read_b128 v[228:231], v74 offset:47616
	ds_read_b32 v236, v75 offset:48128
	v_pk_fma_f32 v[94:95], v[224:225], v[60:61], v[94:95] op_sel_hi:[1,0,1] neg_lo:[1,0,0] neg_hi:[1,0,0]
	v_pk_fma_f32 v[92:93], v[226:227], v[60:61], v[92:93] op_sel_hi:[1,0,1] neg_lo:[1,0,0] neg_hi:[1,0,0]
	v_pk_mul_f32 v[238:239], v[224:225], v[62:63] op_sel_hi:[1,0]
	v_pk_mul_f32 v[240:241], v[226:227], v[62:63] op_sel_hi:[1,0]
	ds_read_b128 v[224:227], v74 offset:47360
	v_pk_mul_f32 v[64:65], v[232:233], v[94:95]
	v_pk_fma_f32 v[88:89], v[88:89], v[216:217], v[238:239] neg_lo:[0,0,1] neg_hi:[0,0,1]
	v_pk_fma_f32 v[90:91], v[90:91], v[218:219], v[240:241] neg_lo:[0,0,1] neg_hi:[0,0,1]
	ds_read_b128 v[216:219], v74 offset:46848
	v_pk_fma_f32 v[64:65], v[234:235], v[92:93], v[64:65]
	v_pk_mul_f32 v[66:67], v[232:233], v[88:89]
	v_pk_fma_f32 v[66:67], v[234:235], v[90:91], v[66:67]
	ds_read_b128 v[232:235], v74 offset:47872
	v_add_f32_e32 v156, v64, v65
	v_add_f32_e32 v177, v66, v67
	s_waitcnt lgkmcnt(6)
	v_pk_mul_f32 v[60:61], v[94:95], v[126:127]
	v_pk_mul_f32 v[62:63], v[88:89], v[126:127]
	v_pk_fma_f32 v[60:61], v[92:93], v[128:129], v[60:61]
	v_pk_fma_f32 v[62:63], v[90:91], v[128:129], v[62:63]
	v_add_f32_e32 v60, v60, v61
	v_add_f32_e32 v62, v62, v63
	v_pk_mul_f32 v[94:95], v[94:95], v[122:123]
	v_pk_mul_f32 v[92:93], v[92:93], v[124:125]
	v_add_f32_dpp v60, v60, v60 quad_perm:[1,0,3,2] row_mask:0xf bank_mask:0xf bound_ctrl:1
	v_add_f32_dpp v62, v62, v62 quad_perm:[1,0,3,2] row_mask:0xf bank_mask:0xf bound_ctrl:1
	v_pk_fma_f32 v[94:95], v[142:143], v[134:135], v[94:95] op_sel_hi:[0,1,1]
	v_add_f32_dpp v60, v60, v60 quad_perm:[2,3,0,1] row_mask:0xf bank_mask:0xf bound_ctrl:1
	v_add_f32_dpp v62, v62, v62 quad_perm:[2,3,0,1] row_mask:0xf bank_mask:0xf bound_ctrl:1
	v_pk_fma_f32 v[92:93], v[142:143], v[136:137], v[92:93] op_sel_hi:[0,1,1]
	v_add_f32_dpp v60, v60, v60 row_half_mirror row_mask:0xf bank_mask:0xf bound_ctrl:1
	v_add_f32_dpp v62, v62, v62 row_half_mirror row_mask:0xf bank_mask:0xf bound_ctrl:1
	ds_read_b128 v[126:129], v74 offset:48640
	v_add_f32_dpp v60, v60, v60 row_mirror row_mask:0xf bank_mask:0xf bound_ctrl:1
	v_add_f32_dpp v62, v62, v62 row_mirror row_mask:0xf bank_mask:0xf bound_ctrl:1
	ds_read_b128 v[134:137], v74 offset:49152
	ds_read_b32 v142, v75 offset:49664
	v_pk_fma_f32 v[94:95], v[130:131], v[60:61], v[94:95] op_sel_hi:[1,0,1] neg_lo:[1,0,0] neg_hi:[1,0,0]
	v_pk_fma_f32 v[92:93], v[132:133], v[60:61], v[92:93] op_sel_hi:[1,0,1] neg_lo:[1,0,0] neg_hi:[1,0,0]
	v_pk_mul_f32 v[238:239], v[130:131], v[62:63] op_sel_hi:[1,0]
	v_pk_mul_f32 v[240:241], v[132:133], v[62:63] op_sel_hi:[1,0]
	ds_read_b128 v[130:133], v74 offset:48896
	v_pk_mul_f32 v[64:65], v[138:139], v[94:95]
	v_pk_fma_f32 v[88:89], v[88:89], v[122:123], v[238:239] neg_lo:[0,0,1] neg_hi:[0,0,1]
	v_pk_fma_f32 v[90:91], v[90:91], v[124:125], v[240:241] neg_lo:[0,0,1] neg_hi:[0,0,1]
	ds_read_b128 v[122:125], v74 offset:48384
	v_pk_fma_f32 v[64:65], v[140:141], v[92:93], v[64:65]
	v_pk_mul_f32 v[66:67], v[138:139], v[88:89]
	v_pk_fma_f32 v[66:67], v[140:141], v[90:91], v[66:67]
	ds_read_b128 v[138:141], v74 offset:49408
	v_add_f32_e32 v157, v64, v65
	v_add_f32_e32 v178, v66, v67
	s_waitcnt lgkmcnt(6)
; template <bool DUAL>
; __device__ __forceinline__ void rwkv_tile(const Params& p, int l, int tile, unsigned char* smem) {
;     ...
;       for (int i = 0; i < 32; ++i) {
;         const int inx = (i + 1) & 31;
;         const float4 nw4 = *(const float4*)(rp + inx * 384), nkk4 = *(const float4*)(rp + inx * 384 + 64), nkb4 = *(const float4*)(rp + inx * 384 + 128);
;         const float4 nkd4 = *(const float4*)(rp + inx * 384 + 192), nr4 = *(const float4*)(rp + inx * 384 + 256);
;         const float nv = vp[inx * 384];
;         v2f t = sA * (v2f){kk4.x, kk4.y};
;         t = sB * (v2f){kk4.z, kk4.w} + t;
;         float sa = t.x + t.y, ia = 0.f;
;         if (DUAL) {
;           v2f ti = iA * (v2f){kk4.x, kk4.y};
;           ti = iB * (v2f){kk4.z, kk4.w} + ti;
;           ia = ti.x + ti.y;
;           sa += dppf<0xB1>(sa); ia += dppf<0xB1>(ia);
;           sa += dppf<0x4E>(sa); ia += dppf<0x4E>(ia);
;           sa += dppf<0x141>(sa); ia += dppf<0x141>(ia);
;           sa += dppf<0x140>(sa); ia += dppf<0x140>(ia);
;         } else {
;           sa = sum16(sa);
;         }
;         v2f cA = sA * (v2f){w4.x, w4.y} + (v2f){kd4.x, kd4.y} * v;
;         v2f cB = sB * (v2f){w4.z, w4.w} + (v2f){kd4.z, kd4.w} * v;
;         sA = cA - (v2f){kb4.x, kb4.y} * sa;
;         sB = cB - (v2f){kb4.z, kb4.w} * sa;
;         v2f u = sA * (v2f){r4.x, r4.y};
;         u = sB * (v2f){r4.z, r4.w} + u;
;         float y = u.x + u.y, g = 0.f;
;         if (DUAL) {
;           iA = iA * (v2f){w4.x, w4.y} - (v2f){kb4.x, kb4.y} * ia;
;           iB = iB * (v2f){w4.z, w4.w} - (v2f){kb4.z, kb4.w} * ia;
;           v2f ui = iA * (v2f){r4.x, r4.y};
;           ui = iB * (v2f){r4.z, r4.w} + ui;
;           g = ui.x + ui.y;
;           y += dppf<0xB1>(y); g += dppf<0xB1>(g);
;           y += dppf<0x4E>(y); g += dppf<0x4E>(g);
;           y += dppf<0x141>(y); g += dppf<0x141>(g);
;           y += dppf<0x140>(y); g += dppf<0x140>(g);
;           if (fr == (i & 15)) gkeep = g;
;         } else {
;           y = sum16(y);
;         }
;         if (fr == (i & 15)) ykeep = y;
	v_pk_mul_f32 v[60:61], v[94:95], v[220:221]
	v_pk_mul_f32 v[62:63], v[88:89], v[220:221]
	v_pk_fma_f32 v[60:61], v[92:93], v[222:223], v[60:61]
	v_pk_fma_f32 v[62:63], v[90:91], v[222:223], v[62:63]
	v_add_f32_e32 v60, v60, v61
	v_add_f32_e32 v62, v62, v63
	v_pk_mul_f32 v[94:95], v[94:95], v[216:217]
	v_pk_mul_f32 v[92:93], v[92:93], v[218:219]
	v_add_f32_dpp v60, v60, v60 quad_perm:[1,0,3,2] row_mask:0xf bank_mask:0xf bound_ctrl:1
	v_add_f32_dpp v62, v62, v62 quad_perm:[1,0,3,2] row_mask:0xf bank_mask:0xf bound_ctrl:1
	v_pk_fma_f32 v[94:95], v[236:237], v[228:229], v[94:95] op_sel_hi:[0,1,1]
	v_add_f32_dpp v60, v60, v60 quad_perm:[2,3,0,1] row_mask:0xf bank_mask:0xf bound_ctrl:1
	v_add_f32_dpp v62, v62, v62 quad_perm:[2,3,0,1] row_mask:0xf bank_mask:0xf bound_ctrl:1
	v_pk_fma_f32 v[92:93], v[236:237], v[230:231], v[92:93] op_sel_hi:[0,1,1]
	v_add_f32_dpp v60, v60, v60 row_half_mirror row_mask:0xf bank_mask:0xf bound_ctrl:1
	v_add_f32_dpp v62, v62, v62 row_half_mirror row_mask:0xf bank_mask:0xf bound_ctrl:1
	ds_read_b128 v[220:223], v69 offset:25600
	v_add_f32_dpp v60, v60, v60 row_mirror row_mask:0xf bank_mask:0xf bound_ctrl:1
	v_add_f32_dpp v62, v62, v62 row_mirror row_mask:0xf bank_mask:0xf bound_ctrl:1
	ds_read_b128 v[228:231], v69 offset:26112
	ds_read_b32 v236, v70 offset:26624
	v_pk_fma_f32 v[94:95], v[224:225], v[60:61], v[94:95] op_sel_hi:[1,0,1] neg_lo:[1,0,0] neg_hi:[1,0,0]
	v_pk_fma_f32 v[92:93], v[226:227], v[60:61], v[92:93] op_sel_hi:[1,0,1] neg_lo:[1,0,0] neg_hi:[1,0,0]
	v_pk_mul_f32 v[238:239], v[224:225], v[62:63] op_sel_hi:[1,0]
	v_pk_mul_f32 v[240:241], v[226:227], v[62:63] op_sel_hi:[1,0]
	ds_read_b128 v[224:227], v69 offset:25856
	v_pk_mul_f32 v[64:65], v[232:233], v[94:95]
	v_pk_fma_f32 v[88:89], v[88:89], v[216:217], v[238:239] neg_lo:[0,0,1] neg_hi:[0,0,1]
	v_pk_fma_f32 v[90:91], v[90:91], v[218:219], v[240:241] neg_lo:[0,0,1] neg_hi:[0,0,1]
	ds_read_b128 v[216:219], v69 offset:25344
	v_pk_fma_f32 v[64:65], v[234:235], v[92:93], v[64:65]
	v_pk_mul_f32 v[66:67], v[232:233], v[88:89]
	v_pk_fma_f32 v[66:67], v[234:235], v[90:91], v[66:67]
	ds_read_b128 v[232:235], v69 offset:26368
	v_add_f32_e32 v158, v64, v65
	v_add_f32_e32 v179, v66, v67
	s_waitcnt lgkmcnt(6)
	v_pk_mul_f32 v[60:61], v[94:95], v[126:127]
	v_pk_mul_f32 v[62:63], v[88:89], v[126:127]
	v_pk_fma_f32 v[60:61], v[92:93], v[128:129], v[60:61]
	v_pk_fma_f32 v[62:63], v[90:91], v[128:129], v[62:63]
	v_add_f32_e32 v60, v60, v61
	v_add_f32_e32 v62, v62, v63
	v_pk_mul_f32 v[94:95], v[94:95], v[122:123]
	v_pk_mul_f32 v[92:93], v[92:93], v[124:125]
	v_add_f32_dpp v60, v60, v60 quad_perm:[1,0,3,2] row_mask:0xf bank_mask:0xf bound_ctrl:1
	v_add_f32_dpp v62, v62, v62 quad_perm:[1,0,3,2] row_mask:0xf bank_mask:0xf bound_ctrl:1
	v_pk_fma_f32 v[94:95], v[142:143], v[134:135], v[94:95] op_sel_hi:[0,1,1]
	v_add_f32_dpp v60, v60, v60 quad_perm:[2,3,0,1] row_mask:0xf bank_mask:0xf bound_ctrl:1
	v_add_f32_dpp v62, v62, v62 quad_perm:[2,3,0,1] row_mask:0xf bank_mask:0xf bound_ctrl:1
	v_pk_fma_f32 v[92:93], v[142:143], v[136:137], v[92:93] op_sel_hi:[0,1,1]
	v_add_f32_dpp v60, v60, v60 row_half_mirror row_mask:0xf bank_mask:0xf bound_ctrl:1
	v_add_f32_dpp v62, v62, v62 row_half_mirror row_mask:0xf bank_mask:0xf bound_ctrl:1
	ds_read_b128 v[126:129], v69 offset:27136
	v_add_f32_dpp v60, v60, v60 row_mirror row_mask:0xf bank_mask:0xf bound_ctrl:1
	v_add_f32_dpp v62, v62, v62 row_mirror row_mask:0xf bank_mask:0xf bound_ctrl:1
	ds_read_b128 v[134:137], v69 offset:27648
	ds_read_b32 v142, v70 offset:28160
	v_pk_fma_f32 v[94:95], v[130:131], v[60:61], v[94:95] op_sel_hi:[1,0,1] neg_lo:[1,0,0] neg_hi:[1,0,0]
	v_pk_fma_f32 v[92:93], v[132:133], v[60:61], v[92:93] op_sel_hi:[1,0,1] neg_lo:[1,0,0] neg_hi:[1,0,0]
	v_pk_mul_f32 v[238:239], v[130:131], v[62:63] op_sel_hi:[1,0]
	v_pk_mul_f32 v[240:241], v[132:133], v[62:63] op_sel_hi:[1,0]
	ds_read_b128 v[130:133], v69 offset:27392
	v_pk_mul_f32 v[64:65], v[138:139], v[94:95]
	v_pk_fma_f32 v[88:89], v[88:89], v[122:123], v[238:239] neg_lo:[0,0,1] neg_hi:[0,0,1]
	v_pk_fma_f32 v[90:91], v[90:91], v[124:125], v[240:241] neg_lo:[0,0,1] neg_hi:[0,0,1]
	ds_read_b128 v[122:125], v69 offset:26880
	v_pk_fma_f32 v[64:65], v[140:141], v[92:93], v[64:65]
	v_pk_mul_f32 v[66:67], v[138:139], v[88:89]
	v_pk_fma_f32 v[66:67], v[140:141], v[90:91], v[66:67]
	ds_read_b128 v[138:141], v69 offset:27904
	v_add_f32_e32 v159, v64, v65
	v_add_f32_e32 v180, v66, v67
	v_add_f32_dpp v144, v144, v144 row_shl:8 row_mask:0xf bank_mask:0x3
	v_add_f32_dpp v144, v152, v152 row_shr:8 row_mask:0xf bank_mask:0xc
	v_add_f32_dpp v145, v145, v145 row_shl:8 row_mask:0xf bank_mask:0x3
	v_add_f32_dpp v145, v153, v153 row_shr:8 row_mask:0xf bank_mask:0xc
	v_add_f32_dpp v146, v146, v146 row_shl:8 row_mask:0xf bank_mask:0x3
	v_add_f32_dpp v146, v154, v154 row_shr:8 row_mask:0xf bank_mask:0xc
	v_add_f32_dpp v147, v147, v147 row_shl:8 row_mask:0xf bank_mask:0x3
	v_add_f32_dpp v147, v155, v155 row_shr:8 row_mask:0xf bank_mask:0xc
	v_add_f32_dpp v148, v148, v148 row_shl:8 row_mask:0xf bank_mask:0x3
	v_add_f32_dpp v148, v156, v156 row_shr:8 row_mask:0xf bank_mask:0xc
	v_add_f32_dpp v149, v149, v149 row_shl:8 row_mask:0xf bank_mask:0x3
	v_add_f32_dpp v149, v157, v157 row_shr:8 row_mask:0xf bank_mask:0xc
	v_add_f32_dpp v150, v150, v150 row_shl:8 row_mask:0xf bank_mask:0x3
	v_add_f32_dpp v150, v158, v158 row_shr:8 row_mask:0xf bank_mask:0xc
	v_add_f32_dpp v151, v151, v151 row_shl:8 row_mask:0xf bank_mask:0x3
	v_add_f32_dpp v151, v159, v159 row_shr:8 row_mask:0xf bank_mask:0xc
	v_add_f32_dpp v144, v144, v144 row_shl:4 row_mask:0xf bank_mask:0x5
	v_add_f32_dpp v144, v148, v148 row_shr:4 row_mask:0xf bank_mask:0xa
; __device__ __forceinline__ bf16_t f2bf(float f) { return (bf16_t)(pack2(f, 0.f) & 0xffffu); }
; template <bool DUAL>
; __device__ __forceinline__ void rwkv_tile(const Params& p, int l, int tile, unsigned char* smem) {
;     ...
;           y += dppf<0xB1>(y); g += dppf<0xB1>(g);
;           y += dppf<0x4E>(y); g += dppf<0x4E>(g);
;           y += dppf<0x141>(y); g += dppf<0x141>(g);
;           y += dppf<0x140>(y); g += dppf<0x140>(g);
;           if (fr == (i & 15)) gkeep = g;
;         } else {
;           y = sum16(y);
;         }
;         if (fr == (i & 15)) ykeep = y;
;         if ((i & 15) == 15) {
;           const int ii = (i & 16) + fr;
;           const int ri = (d == 0) ? ii + 1 : 32 - ii;
;           const int pi = plo - 1 + ri;
;           p.yR[((size_t)d * TOK + rowbase + pi) * 256 + h * 64 + row] = f2bf(ykeep);
;           if (DUAL) p.GID[((size_t)(d * 4 + b) * NSEG1 + (cix - CSPLIT) * 32 + ii) * 256 + h * 64 + row] = f2bf(gkeep);
	v_add_f32_dpp v145, v145, v145 row_shl:4 row_mask:0xf bank_mask:0x5
	v_add_f32_dpp v145, v149, v149 row_shr:4 row_mask:0xf bank_mask:0xa
	v_add_f32_dpp v146, v146, v146 row_shl:4 row_mask:0xf bank_mask:0x5
	v_add_f32_dpp v146, v150, v150 row_shr:4 row_mask:0xf bank_mask:0xa
	v_add_f32_dpp v147, v147, v147 row_shl:4 row_mask:0xf bank_mask:0x5
	v_add_f32_dpp v147, v151, v151 row_shr:4 row_mask:0xf bank_mask:0xa
	v_cndmask_b32_e32 v160, v144, v146, vcc
	v_cndmask_b32_e32 v161, v146, v144, vcc
	v_cndmask_b32_e32 v163, v147, v145, vcc
	v_cndmask_b32_e32 v162, v145, v147, vcc
	v_add_f32_dpp v160, v161, v160 quad_perm:[2,3,0,1] row_mask:0xf bank_mask:0xf
	v_add_f32_dpp v162, v163, v162 quad_perm:[2,3,0,1] row_mask:0xf bank_mask:0xf
	v_cndmask_b32_e64 v181, v160, v162, s[100:101]
	v_cndmask_b32_e64 v182, v162, v160, s[100:101]
	v_add_u32_e32 v74, 0x6000, v74
	v_add_u32_e32 v75, 0x6000, v75
	v_add_f32_dpp v72, v182, v181 quad_perm:[1,0,3,2] row_mask:0xf bank_mask:0xf
	v_add_f32_dpp v165, v165, v165 row_shl:8 row_mask:0xf bank_mask:0x3
	v_add_f32_dpp v165, v173, v173 row_shr:8 row_mask:0xf bank_mask:0xc
	v_add_f32_dpp v166, v166, v166 row_shl:8 row_mask:0xf bank_mask:0x3
	v_add_f32_dpp v166, v174, v174 row_shr:8 row_mask:0xf bank_mask:0xc
	v_add_f32_dpp v167, v167, v167 row_shl:8 row_mask:0xf bank_mask:0x3
	v_add_f32_dpp v167, v175, v175 row_shr:8 row_mask:0xf bank_mask:0xc
	v_add_f32_dpp v168, v168, v168 row_shl:8 row_mask:0xf bank_mask:0x3
	v_add_f32_dpp v168, v176, v176 row_shr:8 row_mask:0xf bank_mask:0xc
	v_add_f32_dpp v169, v169, v169 row_shl:8 row_mask:0xf bank_mask:0x3
	v_add_f32_dpp v169, v177, v177 row_shr:8 row_mask:0xf bank_mask:0xc
	v_add_f32_dpp v170, v170, v170 row_shl:8 row_mask:0xf bank_mask:0x3
	v_add_f32_dpp v170, v178, v178 row_shr:8 row_mask:0xf bank_mask:0xc
	v_add_f32_dpp v171, v171, v171 row_shl:8 row_mask:0xf bank_mask:0x3
	v_add_f32_dpp v171, v179, v179 row_shr:8 row_mask:0xf bank_mask:0xc
	v_add_f32_dpp v172, v172, v172 row_shl:8 row_mask:0xf bank_mask:0x3
	v_add_f32_dpp v172, v180, v180 row_shr:8 row_mask:0xf bank_mask:0xc
	v_add_f32_dpp v165, v165, v165 row_shl:4 row_mask:0xf bank_mask:0x5
	v_add_f32_dpp v165, v169, v169 row_shr:4 row_mask:0xf bank_mask:0xa
	v_add_f32_dpp v166, v166, v166 row_shl:4 row_mask:0xf bank_mask:0x5
	v_add_f32_dpp v166, v170, v170 row_shr:4 row_mask:0xf bank_mask:0xa
	v_add_f32_dpp v167, v167, v167 row_shl:4 row_mask:0xf bank_mask:0x5
	v_add_f32_dpp v167, v171, v171 row_shr:4 row_mask:0xf bank_mask:0xa
	v_add_f32_dpp v168, v168, v168 row_shl:4 row_mask:0xf bank_mask:0x5
	v_add_f32_dpp v168, v172, v172 row_shr:4 row_mask:0xf bank_mask:0xa
	v_cndmask_b32_e32 v160, v165, v167, vcc
	v_cndmask_b32_e32 v161, v167, v165, vcc
	v_cndmask_b32_e32 v163, v168, v166, vcc
	v_cndmask_b32_e32 v162, v166, v168, vcc
	v_add_f32_dpp v160, v161, v160 quad_perm:[2,3,0,1] row_mask:0xf bank_mask:0xf
	v_add_f32_dpp v162, v163, v162 quad_perm:[2,3,0,1] row_mask:0xf bank_mask:0xf
	v_cndmask_b32_e64 v181, v160, v162, s[100:101]
	v_cndmask_b32_e64 v182, v162, v160, s[100:101]
	v_mov_b32_e32 v69, v102
	v_mov_b32_e32 v70, v103
	v_add_f32_dpp v73, v182, v181 quad_perm:[1,0,3,2] row_mask:0xf bank_mask:0xf
	v_mov_b32_e32 v79, v68
	v_add_u32_e32 v77, 1, v79
	v_sub_u32_e32 v76, 32, v79
	v_cndmask_b32_e64 v76, v76, v77, s[36:37]
	v_add_u32_e32 v76, s28, v76
	v_ashrrev_i32_e32 v77, 31, v76
	v_lshl_add_u64 v[76:77], s[20:21], 0, v[76:77]
	v_lshlrev_b64 v[76:77], 9, v[76:77]
	v_cvt_pk_bf16_f32 v78, v72, v72
	v_lshl_add_u64 v[76:77], v[84:85], 0, v[76:77]
	global_store_short v[76:77], v78, off
	v_or_b32_e32 v76, s53, v79
	v_mov_b32_e32 v77, s54
	v_cvt_pk_bf16_f32 v79, v73, v73
	v_lshlrev_b64 v[76:77], 9, v[76:77]
	v_lshl_add_u64 v[76:77], v[86:87], 0, v[76:77]
	global_store_short v[76:77], v79, off
	v_add_u32_e32 v68, 16, v68
	s_add_i32 s55, s55, 1
	s_cmp_lg_u32 s55, 2
	s_cbranch_scc1 .Lrw_du_loop
	s_branch .LBB0_1436
.Lrw_nd_scan:
	v_mov_b32_e32 v72, v99
	v_mov_b32_e32 v73, v100
	v_add_u32_e32 v68, 0x6000, v99
	v_add_u32_e32 v69, 0x6000, v100
	v_mov_b32_e32 v71, v98
	s_mov_b32 vcc_lo, 0xcccccccc
	s_mov_b32 vcc_hi, 0xcccccccc
	s_mov_b32 s100, 0xaaaaaaaa
	s_mov_b32 s101, 0xaaaaaaaa
	ds_read_b128 v[220:223], v72 offset:25600
	ds_read_b128 v[216:219], v72 offset:25344
	ds_read_b128 v[228:231], v72 offset:26112
	ds_read_b32 v236, v73 offset:26624
	ds_read_b128 v[224:227], v72 offset:25856
	ds_read_b128 v[232:235], v72 offset:26368
	ds_read_b128 v[122:125], v72 offset:27136
	ds_read_b128 v[118:121], v72 offset:26880
	ds_read_b128 v[130:133], v72 offset:27648
	ds_read_b32 v138, v73 offset:28160
	ds_read_b128 v[126:129], v72 offset:27392
	ds_read_b128 v[134:137], v72 offset:27904
	s_mov_b32 s50, 0
; template <bool DUAL>
; __device__ __forceinline__ void rwkv_tile(const Params& p, int l, int tile, unsigned char* smem) {
;     ...
; #pragma unroll 2
;       for (int i = 0; i < 32; ++i) {
;         const int inx = (i + 1) & 31;
;         const float4 nw4 = *(const float4*)(rp + inx * 384), nkk4 = *(const float4*)(rp + inx * 384 + 64), nkb4 = *(const float4*)(rp + inx * 384 + 128);
;         const float4 nkd4 = *(const float4*)(rp + inx * 384 + 192), nr4 = *(const float4*)(rp + inx * 384 + 256);
;         const float nv = vp[inx * 384];
;         v2f t = sA * (v2f){kk4.x, kk4.y};
;         t = sB * (v2f){kk4.z, kk4.w} + t;
;         float sa = t.x + t.y, ia = 0.f;
;         if (DUAL) {
;           v2f ti = iA * (v2f){kk4.x, kk4.y};
;           ti = iB * (v2f){kk4.z, kk4.w} + ti;
;           ia = ti.x + ti.y;
;           sa += dppf<0xB1>(sa); ia += dppf<0xB1>(ia);
;           sa += dppf<0x4E>(sa); ia += dppf<0x4E>(ia);
;           sa += dppf<0x141>(sa); ia += dppf<0x141>(ia);
;           sa += dppf<0x140>(sa); ia += dppf<0x140>(ia);
;         } else {
;           sa = sum16(sa);
;         }
;         v2f cA = sA * (v2f){w4.x, w4.y} + (v2f){kd4.x, kd4.y} * v;
;         v2f cB = sB * (v2f){w4.z, w4.w} + (v2f){kd4.z, kd4.w} * v;
;         sA = cA - (v2f){kb4.x, kb4.y} * sa;
;         sB = cB - (v2f){kb4.z, kb4.w} * sa;
;         v2f u = sA * (v2f){r4.x, r4.y};
;         u = sB * (v2f){r4.z, r4.w} + u;
;         float y = u.x + u.y, g = 0.f;
;         if (DUAL) {
;           iA = iA * (v2f){w4.x, w4.y} - (v2f){kb4.x, kb4.y} * ia;
;           iB = iB * (v2f){w4.z, w4.w} - (v2f){kb4.z, kb4.w} * ia;
;           v2f ui = iA * (v2f){r4.x, r4.y};
;           ui = iB * (v2f){r4.z, r4.w} + ui;
;           g = ui.x + ui.y;
;           y += dppf<0xB1>(y); g += dppf<0xB1>(g);
;           y += dppf<0x4E>(y); g += dppf<0x4E>(g);
;           y += dppf<0x141>(y); g += dppf<0x141>(g);
;           y += dppf<0x140>(y); g += dppf<0x140>(g);
;           if (fr == (i & 15)) gkeep = g;
;         } else {
;           y = sum16(y);
;         }
;         if (fr == (i & 15)) ykeep = y;
.Lrw_nd_loop:
	s_waitcnt lgkmcnt(6)
	v_pk_mul_f32 v[64:65], v[60:61], v[220:221]
	v_pk_fma_f32 v[64:65], v[62:63], v[222:223], v[64:65]
	v_add_f32_e32 v64, v64, v65
	v_pk_mul_f32 v[60:61], v[60:61], v[216:217]
	v_pk_mul_f32 v[62:63], v[62:63], v[218:219]
	v_add_f32_dpp v64, v64, v64 quad_perm:[1,0,3,2] row_mask:0xf bank_mask:0xf bound_ctrl:1
	v_pk_fma_f32 v[60:61], v[236:237], v[228:229], v[60:61] op_sel_hi:[0,1,1]
	v_pk_fma_f32 v[62:63], v[236:237], v[230:231], v[62:63] op_sel_hi:[0,1,1]
	v_add_f32_dpp v64, v64, v64 quad_perm:[2,3,0,1] row_mask:0xf bank_mask:0xf bound_ctrl:1
	ds_read_b128 v[220:223], v72 offset:28672
	ds_read_b128 v[216:219], v72 offset:28416
	v_add_f32_dpp v64, v64, v64 row_half_mirror row_mask:0xf bank_mask:0xf bound_ctrl:1
	ds_read_b128 v[228:231], v72 offset:29184
	ds_read_b32 v236, v73 offset:29696
	v_add_f32_dpp v64, v64, v64 row_mirror row_mask:0xf bank_mask:0xf bound_ctrl:1
	v_pk_fma_f32 v[60:61], v[224:225], v[64:65], v[60:61] op_sel_hi:[1,0,1] neg_lo:[1,0,0] neg_hi:[1,0,0]
	v_pk_fma_f32 v[62:63], v[226:227], v[64:65], v[62:63] op_sel_hi:[1,0,1] neg_lo:[1,0,0] neg_hi:[1,0,0]
	ds_read_b128 v[224:227], v72 offset:28928
	v_pk_mul_f32 v[66:67], v[232:233], v[60:61]
	v_pk_fma_f32 v[66:67], v[234:235], v[62:63], v[66:67]
	ds_read_b128 v[232:235], v72 offset:29440
	v_add_f32_e32 v140, v66, v67
	s_waitcnt lgkmcnt(6)
	v_pk_mul_f32 v[64:65], v[60:61], v[122:123]
	v_pk_fma_f32 v[64:65], v[62:63], v[124:125], v[64:65]
	v_add_f32_e32 v64, v64, v65
	v_pk_mul_f32 v[60:61], v[60:61], v[118:119]
	v_pk_mul_f32 v[62:63], v[62:63], v[120:121]
	v_add_f32_dpp v64, v64, v64 quad_perm:[1,0,3,2] row_mask:0xf bank_mask:0xf bound_ctrl:1
	v_pk_fma_f32 v[60:61], v[138:139], v[130:131], v[60:61] op_sel_hi:[0,1,1]
	v_pk_fma_f32 v[62:63], v[138:139], v[132:133], v[62:63] op_sel_hi:[0,1,1]
	v_add_f32_dpp v64, v64, v64 quad_perm:[2,3,0,1] row_mask:0xf bank_mask:0xf bound_ctrl:1
	ds_read_b128 v[122:125], v72 offset:30208
	ds_read_b128 v[118:121], v72 offset:29952
	v_add_f32_dpp v64, v64, v64 row_half_mirror row_mask:0xf bank_mask:0xf bound_ctrl:1
	ds_read_b128 v[130:133], v72 offset:30720
	ds_read_b32 v138, v73 offset:31232
	v_add_f32_dpp v64, v64, v64 row_mirror row_mask:0xf bank_mask:0xf bound_ctrl:1
	v_pk_fma_f32 v[60:61], v[126:127], v[64:65], v[60:61] op_sel_hi:[1,0,1] neg_lo:[1,0,0] neg_hi:[1,0,0]
	v_pk_fma_f32 v[62:63], v[128:129], v[64:65], v[62:63] op_sel_hi:[1,0,1] neg_lo:[1,0,0] neg_hi:[1,0,0]
	ds_read_b128 v[126:129], v72 offset:30464
	v_pk_mul_f32 v[66:67], v[134:135], v[60:61]
	v_pk_fma_f32 v[66:67], v[136:137], v[62:63], v[66:67]
	ds_read_b128 v[134:137], v72 offset:30976
	v_add_f32_e32 v141, v66, v67
	s_waitcnt lgkmcnt(6)
	v_pk_mul_f32 v[64:65], v[60:61], v[220:221]
	v_pk_fma_f32 v[64:65], v[62:63], v[222:223], v[64:65]
	v_add_f32_e32 v64, v64, v65
	v_pk_mul_f32 v[60:61], v[60:61], v[216:217]
	v_pk_mul_f32 v[62:63], v[62:63], v[218:219]
	v_add_f32_dpp v64, v64, v64 quad_perm:[1,0,3,2] row_mask:0xf bank_mask:0xf bound_ctrl:1
	v_pk_fma_f32 v[60:61], v[236:237], v[228:229], v[60:61] op_sel_hi:[0,1,1]
	v_pk_fma_f32 v[62:63], v[236:237], v[230:231], v[62:63] op_sel_hi:[0,1,1]
	v_add_f32_dpp v64, v64, v64 quad_perm:[2,3,0,1] row_mask:0xf bank_mask:0xf bound_ctrl:1
	ds_read_b128 v[220:223], v72 offset:31744
	ds_read_b128 v[216:219], v72 offset:31488
	v_add_f32_dpp v64, v64, v64 row_half_mirror row_mask:0xf bank_mask:0xf bound_ctrl:1
	ds_read_b128 v[228:231], v72 offset:32256
	ds_read_b32 v236, v73 offset:32768
	v_add_f32_dpp v64, v64, v64 row_mirror row_mask:0xf bank_mask:0xf bound_ctrl:1
	v_pk_fma_f32 v[60:61], v[224:225], v[64:65], v[60:61] op_sel_hi:[1,0,1] neg_lo:[1,0,0] neg_hi:[1,0,0]
	v_pk_fma_f32 v[62:63], v[226:227], v[64:65], v[62:63] op_sel_hi:[1,0,1] neg_lo:[1,0,0] neg_hi:[1,0,0]
	ds_read_b128 v[224:227], v72 offset:32000
	v_pk_mul_f32 v[66:67], v[232:233], v[60:61]
	v_pk_fma_f32 v[66:67], v[234:235], v[62:63], v[66:67]
	ds_read_b128 v[232:235], v72 offset:32512
	v_add_f32_e32 v142, v66, v67
	s_waitcnt lgkmcnt(6)
	v_pk_mul_f32 v[64:65], v[60:61], v[122:123]
	v_pk_fma_f32 v[64:65], v[62:63], v[124:125], v[64:65]
	v_add_f32_e32 v64, v64, v65
	v_pk_mul_f32 v[60:61], v[60:61], v[118:119]
	v_pk_mul_f32 v[62:63], v[62:63], v[120:121]
	v_add_f32_dpp v64, v64, v64 quad_perm:[1,0,3,2] row_mask:0xf bank_mask:0xf bound_ctrl:1
	v_pk_fma_f32 v[60:61], v[138:139], v[130:131], v[60:61] op_sel_hi:[0,1,1]
	v_pk_fma_f32 v[62:63], v[138:139], v[132:133], v[62:63] op_sel_hi:[0,1,1]
	v_add_f32_dpp v64, v64, v64 quad_perm:[2,3,0,1] row_mask:0xf bank_mask:0xf bound_ctrl:1
	ds_read_b128 v[122:125], v72 offset:33280
	ds_read_b128 v[118:121], v72 offset:33024
	v_add_f32_dpp v64, v64, v64 row_half_mirror row_mask:0xf bank_mask:0xf bound_ctrl:1
	ds_read_b128 v[130:133], v72 offset:33792
	ds_read_b32 v138, v73 offset:34304
	v_add_f32_dpp v64, v64, v64 row_mirror row_mask:0xf bank_mask:0xf bound_ctrl:1
	v_pk_fma_f32 v[60:61], v[126:127], v[64:65], v[60:61] op_sel_hi:[1,0,1] neg_lo:[1,0,0] neg_hi:[1,0,0]
	v_pk_fma_f32 v[62:63], v[128:129], v[64:65], v[62:63] op_sel_hi:[1,0,1] neg_lo:[1,0,0] neg_hi:[1,0,0]
	ds_read_b128 v[126:129], v72 offset:33536
	v_pk_mul_f32 v[66:67], v[134:135], v[60:61]
	v_pk_fma_f32 v[66:67], v[136:137], v[62:63], v[66:67]
	ds_read_b128 v[134:137], v72 offset:34048
	v_add_f32_e32 v143, v66, v67
	s_waitcnt lgkmcnt(6)
; template <bool DUAL>
; __device__ __forceinline__ void rwkv_tile(const Params& p, int l, int tile, unsigned char* smem) {
;     ...
; #pragma unroll 2
;       for (int i = 0; i < 32; ++i) {
;         const int inx = (i + 1) & 31;
;         const float4 nw4 = *(const float4*)(rp + inx * 384), nkk4 = *(const float4*)(rp + inx * 384 + 64), nkb4 = *(const float4*)(rp + inx * 384 + 128);
;         const float4 nkd4 = *(const float4*)(rp + inx * 384 + 192), nr4 = *(const float4*)(rp + inx * 384 + 256);
;         const float nv = vp[inx * 384];
;         v2f t = sA * (v2f){kk4.x, kk4.y};
;         t = sB * (v2f){kk4.z, kk4.w} + t;
;         float sa = t.x + t.y, ia = 0.f;
;         if (DUAL) {
;           v2f ti = iA * (v2f){kk4.x, kk4.y};
;           ti = iB * (v2f){kk4.z, kk4.w} + ti;
;           ia = ti.x + ti.y;
;           sa += dppf<0xB1>(sa); ia += dppf<0xB1>(ia);
;           sa += dppf<0x4E>(sa); ia += dppf<0x4E>(ia);
;           sa += dppf<0x141>(sa); ia += dppf<0x141>(ia);
;           sa += dppf<0x140>(sa); ia += dppf<0x140>(ia);
;         } else {
;           sa = sum16(sa);
;         }
;         v2f cA = sA * (v2f){w4.x, w4.y} + (v2f){kd4.x, kd4.y} * v;
;         v2f cB = sB * (v2f){w4.z, w4.w} + (v2f){kd4.z, kd4.w} * v;
;         sA = cA - (v2f){kb4.x, kb4.y} * sa;
;         sB = cB - (v2f){kb4.z, kb4.w} * sa;
;         v2f u = sA * (v2f){r4.x, r4.y};
;         u = sB * (v2f){r4.z, r4.w} + u;
;         float y = u.x + u.y, g = 0.f;
;         if (DUAL) {
;           iA = iA * (v2f){w4.x, w4.y} - (v2f){kb4.x, kb4.y} * ia;
;           iB = iB * (v2f){w4.z, w4.w} - (v2f){kb4.z, kb4.w} * ia;
;           v2f ui = iA * (v2f){r4.x, r4.y};
;           ui = iB * (v2f){r4.z, r4.w} + ui;
;           g = ui.x + ui.y;
;           y += dppf<0xB1>(y); g += dppf<0xB1>(g);
;           y += dppf<0x4E>(y); g += dppf<0x4E>(g);
;           y += dppf<0x141>(y); g += dppf<0x141>(g);
;           y += dppf<0x140>(y); g += dppf<0x140>(g);
;           if (fr == (i & 15)) gkeep = g;
;         } else {
;           y = sum16(y);
;         }
;         if (fr == (i & 15)) ykeep = y;
	v_pk_mul_f32 v[64:65], v[60:61], v[220:221]
	v_pk_fma_f32 v[64:65], v[62:63], v[222:223], v[64:65]
	v_add_f32_e32 v64, v64, v65
	v_pk_mul_f32 v[60:61], v[60:61], v[216:217]
	v_pk_mul_f32 v[62:63], v[62:63], v[218:219]
	v_add_f32_dpp v64, v64, v64 quad_perm:[1,0,3,2] row_mask:0xf bank_mask:0xf bound_ctrl:1
	v_pk_fma_f32 v[60:61], v[236:237], v[228:229], v[60:61] op_sel_hi:[0,1,1]
	v_pk_fma_f32 v[62:63], v[236:237], v[230:231], v[62:63] op_sel_hi:[0,1,1]
	v_add_f32_dpp v64, v64, v64 quad_perm:[2,3,0,1] row_mask:0xf bank_mask:0xf bound_ctrl:1
	ds_read_b128 v[220:223], v72 offset:34816
	ds_read_b128 v[216:219], v72 offset:34560
	v_add_f32_dpp v64, v64, v64 row_half_mirror row_mask:0xf bank_mask:0xf bound_ctrl:1
	ds_read_b128 v[228:231], v72 offset:35328
	ds_read_b32 v236, v73 offset:35840
	v_add_f32_dpp v64, v64, v64 row_mirror row_mask:0xf bank_mask:0xf bound_ctrl:1
	v_pk_fma_f32 v[60:61], v[224:225], v[64:65], v[60:61] op_sel_hi:[1,0,1] neg_lo:[1,0,0] neg_hi:[1,0,0]
	v_pk_fma_f32 v[62:63], v[226:227], v[64:65], v[62:63] op_sel_hi:[1,0,1] neg_lo:[1,0,0] neg_hi:[1,0,0]
	ds_read_b128 v[224:227], v72 offset:35072
	v_pk_mul_f32 v[66:67], v[232:233], v[60:61]
	v_pk_fma_f32 v[66:67], v[234:235], v[62:63], v[66:67]
	ds_read_b128 v[232:235], v72 offset:35584
	v_add_f32_e32 v144, v66, v67
	s_waitcnt lgkmcnt(6)
	v_pk_mul_f32 v[64:65], v[60:61], v[122:123]
	v_pk_fma_f32 v[64:65], v[62:63], v[124:125], v[64:65]
	v_add_f32_e32 v64, v64, v65
	v_pk_mul_f32 v[60:61], v[60:61], v[118:119]
	v_pk_mul_f32 v[62:63], v[62:63], v[120:121]
	v_add_f32_dpp v64, v64, v64 quad_perm:[1,0,3,2] row_mask:0xf bank_mask:0xf bound_ctrl:1
	v_pk_fma_f32 v[60:61], v[138:139], v[130:131], v[60:61] op_sel_hi:[0,1,1]
	v_pk_fma_f32 v[62:63], v[138:139], v[132:133], v[62:63] op_sel_hi:[0,1,1]
	v_add_f32_dpp v64, v64, v64 quad_perm:[2,3,0,1] row_mask:0xf bank_mask:0xf bound_ctrl:1
	ds_read_b128 v[122:125], v72 offset:36352
	ds_read_b128 v[118:121], v72 offset:36096
	v_add_f32_dpp v64, v64, v64 row_half_mirror row_mask:0xf bank_mask:0xf bound_ctrl:1
	ds_read_b128 v[130:133], v72 offset:36864
	ds_read_b32 v138, v73 offset:37376
	v_add_f32_dpp v64, v64, v64 row_mirror row_mask:0xf bank_mask:0xf bound_ctrl:1
	v_pk_fma_f32 v[60:61], v[126:127], v[64:65], v[60:61] op_sel_hi:[1,0,1] neg_lo:[1,0,0] neg_hi:[1,0,0]
	v_pk_fma_f32 v[62:63], v[128:129], v[64:65], v[62:63] op_sel_hi:[1,0,1] neg_lo:[1,0,0] neg_hi:[1,0,0]
	ds_read_b128 v[126:129], v72 offset:36608
	v_pk_mul_f32 v[66:67], v[134:135], v[60:61]
	v_pk_fma_f32 v[66:67], v[136:137], v[62:63], v[66:67]
	ds_read_b128 v[134:137], v72 offset:37120
	v_add_f32_e32 v145, v66, v67
	s_waitcnt lgkmcnt(6)
	v_pk_mul_f32 v[64:65], v[60:61], v[220:221]
	v_pk_fma_f32 v[64:65], v[62:63], v[222:223], v[64:65]
	v_add_f32_e32 v64, v64, v65
	v_pk_mul_f32 v[60:61], v[60:61], v[216:217]
	v_pk_mul_f32 v[62:63], v[62:63], v[218:219]
	v_add_f32_dpp v64, v64, v64 quad_perm:[1,0,3,2] row_mask:0xf bank_mask:0xf bound_ctrl:1
	v_pk_fma_f32 v[60:61], v[236:237], v[228:229], v[60:61] op_sel_hi:[0,1,1]
	v_pk_fma_f32 v[62:63], v[236:237], v[230:231], v[62:63] op_sel_hi:[0,1,1]
	v_add_f32_dpp v64, v64, v64 quad_perm:[2,3,0,1] row_mask:0xf bank_mask:0xf bound_ctrl:1
	ds_read_b128 v[220:223], v72 offset:37888
	ds_read_b128 v[216:219], v72 offset:37632
	v_add_f32_dpp v64, v64, v64 row_half_mirror row_mask:0xf bank_mask:0xf bound_ctrl:1
	ds_read_b128 v[228:231], v72 offset:38400
	ds_read_b32 v236, v73 offset:38912
	v_add_f32_dpp v64, v64, v64 row_mirror row_mask:0xf bank_mask:0xf bound_ctrl:1
	v_pk_fma_f32 v[60:61], v[224:225], v[64:65], v[60:61] op_sel_hi:[1,0,1] neg_lo:[1,0,0] neg_hi:[1,0,0]
	v_pk_fma_f32 v[62:63], v[226:227], v[64:65], v[62:63] op_sel_hi:[1,0,1] neg_lo:[1,0,0] neg_hi:[1,0,0]
	ds_read_b128 v[224:227], v72 offset:38144
	v_pk_mul_f32 v[66:67], v[232:233], v[60:61]
	v_pk_fma_f32 v[66:67], v[234:235], v[62:63], v[66:67]
	ds_read_b128 v[232:235], v72 offset:38656
	v_add_f32_e32 v146, v66, v67
	s_waitcnt lgkmcnt(6)
	v_pk_mul_f32 v[64:65], v[60:61], v[122:123]
	v_pk_fma_f32 v[64:65], v[62:63], v[124:125], v[64:65]
	v_add_f32_e32 v64, v64, v65
	v_pk_mul_f32 v[60:61], v[60:61], v[118:119]
	v_pk_mul_f32 v[62:63], v[62:63], v[120:121]
	v_add_f32_dpp v64, v64, v64 quad_perm:[1,0,3,2] row_mask:0xf bank_mask:0xf bound_ctrl:1
	v_pk_fma_f32 v[60:61], v[138:139], v[130:131], v[60:61] op_sel_hi:[0,1,1]
	v_pk_fma_f32 v[62:63], v[138:139], v[132:133], v[62:63] op_sel_hi:[0,1,1]
	v_add_f32_dpp v64, v64, v64 quad_perm:[2,3,0,1] row_mask:0xf bank_mask:0xf bound_ctrl:1
	ds_read_b128 v[122:125], v72 offset:39424
	ds_read_b128 v[118:121], v72 offset:39168
	v_add_f32_dpp v64, v64, v64 row_half_mirror row_mask:0xf bank_mask:0xf bound_ctrl:1
	ds_read_b128 v[130:133], v72 offset:39936
	ds_read_b32 v138, v73 offset:40448
	v_add_f32_dpp v64, v64, v64 row_mirror row_mask:0xf bank_mask:0xf bound_ctrl:1
	v_pk_fma_f32 v[60:61], v[126:127], v[64:65], v[60:61] op_sel_hi:[1,0,1] neg_lo:[1,0,0] neg_hi:[1,0,0]
	v_pk_fma_f32 v[62:63], v[128:129], v[64:65], v[62:63] op_sel_hi:[1,0,1] neg_lo:[1,0,0] neg_hi:[1,0,0]
	ds_read_b128 v[126:129], v72 offset:39680
	v_pk_mul_f32 v[66:67], v[134:135], v[60:61]
	v_pk_fma_f32 v[66:67], v[136:137], v[62:63], v[66:67]
	ds_read_b128 v[134:137], v72 offset:40192
	v_add_f32_e32 v147, v66, v67
	s_waitcnt lgkmcnt(6)
; template <bool DUAL>
; __device__ __forceinline__ void rwkv_tile(const Params& p, int l, int tile, unsigned char* smem) {
;     ...
; #pragma unroll 2
;       for (int i = 0; i < 32; ++i) {
;         const int inx = (i + 1) & 31;
;         const float4 nw4 = *(const float4*)(rp + inx * 384), nkk4 = *(const float4*)(rp + inx * 384 + 64), nkb4 = *(const float4*)(rp + inx * 384 + 128);
;         const float4 nkd4 = *(const float4*)(rp + inx * 384 + 192), nr4 = *(const float4*)(rp + inx * 384 + 256);
;         const float nv = vp[inx * 384];
;         v2f t = sA * (v2f){kk4.x, kk4.y};
;         t = sB * (v2f){kk4.z, kk4.w} + t;
;         float sa = t.x + t.y, ia = 0.f;
;         if (DUAL) {
;           v2f ti = iA * (v2f){kk4.x, kk4.y};
;           ti = iB * (v2f){kk4.z, kk4.w} + ti;
;           ia = ti.x + ti.y;
;           sa += dppf<0xB1>(sa); ia += dppf<0xB1>(ia);
;           sa += dppf<0x4E>(sa); ia += dppf<0x4E>(ia);
;           sa += dppf<0x141>(sa); ia += dppf<0x141>(ia);
;           sa += dppf<0x140>(sa); ia += dppf<0x140>(ia);
;         } else {
;           sa = sum16(sa);
;         }
;         v2f cA = sA * (v2f){w4.x, w4.y} + (v2f){kd4.x, kd4.y} * v;
;         v2f cB = sB * (v2f){w4.z, w4.w} + (v2f){kd4.z, kd4.w} * v;
;         sA = cA - (v2f){kb4.x, kb4.y} * sa;
;         sB = cB - (v2f){kb4.z, kb4.w} * sa;
;         v2f u = sA * (v2f){r4.x, r4.y};
;         u = sB * (v2f){r4.z, r4.w} + u;
;         float y = u.x + u.y, g = 0.f;
;         if (DUAL) {
;           iA = iA * (v2f){w4.x, w4.y} - (v2f){kb4.x, kb4.y} * ia;
;           iB = iB * (v2f){w4.z, w4.w} - (v2f){kb4.z, kb4.w} * ia;
;           v2f ui = iA * (v2f){r4.x, r4.y};
;           ui = iB * (v2f){r4.z, r4.w} + ui;
;           g = ui.x + ui.y;
;           y += dppf<0xB1>(y); g += dppf<0xB1>(g);
;           y += dppf<0x4E>(y); g += dppf<0x4E>(g);
;           y += dppf<0x141>(y); g += dppf<0x141>(g);
;           y += dppf<0x140>(y); g += dppf<0x140>(g);
;           if (fr == (i & 15)) gkeep = g;
;         } else {
;           y = sum16(y);
;         }
;         if (fr == (i & 15)) ykeep = y;
	v_pk_mul_f32 v[64:65], v[60:61], v[220:221]
	v_pk_fma_f32 v[64:65], v[62:63], v[222:223], v[64:65]
	v_add_f32_e32 v64, v64, v65
	v_pk_mul_f32 v[60:61], v[60:61], v[216:217]
	v_pk_mul_f32 v[62:63], v[62:63], v[218:219]
	v_add_f32_dpp v64, v64, v64 quad_perm:[1,0,3,2] row_mask:0xf bank_mask:0xf bound_ctrl:1
	v_pk_fma_f32 v[60:61], v[236:237], v[228:229], v[60:61] op_sel_hi:[0,1,1]
	v_pk_fma_f32 v[62:63], v[236:237], v[230:231], v[62:63] op_sel_hi:[0,1,1]
	v_add_f32_dpp v64, v64, v64 quad_perm:[2,3,0,1] row_mask:0xf bank_mask:0xf bound_ctrl:1
	ds_read_b128 v[220:223], v72 offset:40960
	ds_read_b128 v[216:219], v72 offset:40704
	v_add_f32_dpp v64, v64, v64 row_half_mirror row_mask:0xf bank_mask:0xf bound_ctrl:1
	ds_read_b128 v[228:231], v72 offset:41472
	ds_read_b32 v236, v73 offset:41984
	v_add_f32_dpp v64, v64, v64 row_mirror row_mask:0xf bank_mask:0xf bound_ctrl:1
	v_pk_fma_f32 v[60:61], v[224:225], v[64:65], v[60:61] op_sel_hi:[1,0,1] neg_lo:[1,0,0] neg_hi:[1,0,0]
	v_pk_fma_f32 v[62:63], v[226:227], v[64:65], v[62:63] op_sel_hi:[1,0,1] neg_lo:[1,0,0] neg_hi:[1,0,0]
	ds_read_b128 v[224:227], v72 offset:41216
	v_pk_mul_f32 v[66:67], v[232:233], v[60:61]
	v_pk_fma_f32 v[66:67], v[234:235], v[62:63], v[66:67]
	ds_read_b128 v[232:235], v72 offset:41728
	v_add_f32_e32 v148, v66, v67
	s_waitcnt lgkmcnt(6)
	v_pk_mul_f32 v[64:65], v[60:61], v[122:123]
	v_pk_fma_f32 v[64:65], v[62:63], v[124:125], v[64:65]
	v_add_f32_e32 v64, v64, v65
	v_pk_mul_f32 v[60:61], v[60:61], v[118:119]
	v_pk_mul_f32 v[62:63], v[62:63], v[120:121]
	v_add_f32_dpp v64, v64, v64 quad_perm:[1,0,3,2] row_mask:0xf bank_mask:0xf bound_ctrl:1
	v_pk_fma_f32 v[60:61], v[138:139], v[130:131], v[60:61] op_sel_hi:[0,1,1]
	v_pk_fma_f32 v[62:63], v[138:139], v[132:133], v[62:63] op_sel_hi:[0,1,1]
	v_add_f32_dpp v64, v64, v64 quad_perm:[2,3,0,1] row_mask:0xf bank_mask:0xf bound_ctrl:1
	ds_read_b128 v[122:125], v72 offset:42496
	ds_read_b128 v[118:121], v72 offset:42240
	v_add_f32_dpp v64, v64, v64 row_half_mirror row_mask:0xf bank_mask:0xf bound_ctrl:1
	ds_read_b128 v[130:133], v72 offset:43008
	ds_read_b32 v138, v73 offset:43520
	v_add_f32_dpp v64, v64, v64 row_mirror row_mask:0xf bank_mask:0xf bound_ctrl:1
	v_pk_fma_f32 v[60:61], v[126:127], v[64:65], v[60:61] op_sel_hi:[1,0,1] neg_lo:[1,0,0] neg_hi:[1,0,0]
	v_pk_fma_f32 v[62:63], v[128:129], v[64:65], v[62:63] op_sel_hi:[1,0,1] neg_lo:[1,0,0] neg_hi:[1,0,0]
	ds_read_b128 v[126:129], v72 offset:42752
	v_pk_mul_f32 v[66:67], v[134:135], v[60:61]
	v_pk_fma_f32 v[66:67], v[136:137], v[62:63], v[66:67]
	ds_read_b128 v[134:137], v72 offset:43264
	v_add_f32_e32 v149, v66, v67
	s_waitcnt lgkmcnt(6)
	v_pk_mul_f32 v[64:65], v[60:61], v[220:221]
	v_pk_fma_f32 v[64:65], v[62:63], v[222:223], v[64:65]
	v_add_f32_e32 v64, v64, v65
	v_pk_mul_f32 v[60:61], v[60:61], v[216:217]
	v_pk_mul_f32 v[62:63], v[62:63], v[218:219]
	v_add_f32_dpp v64, v64, v64 quad_perm:[1,0,3,2] row_mask:0xf bank_mask:0xf bound_ctrl:1
	v_pk_fma_f32 v[60:61], v[236:237], v[228:229], v[60:61] op_sel_hi:[0,1,1]
	v_pk_fma_f32 v[62:63], v[236:237], v[230:231], v[62:63] op_sel_hi:[0,1,1]
	v_add_f32_dpp v64, v64, v64 quad_perm:[2,3,0,1] row_mask:0xf bank_mask:0xf bound_ctrl:1
	ds_read_b128 v[220:223], v72 offset:44032
	ds_read_b128 v[216:219], v72 offset:43776
	v_add_f32_dpp v64, v64, v64 row_half_mirror row_mask:0xf bank_mask:0xf bound_ctrl:1
	ds_read_b128 v[228:231], v72 offset:44544
	ds_read_b32 v236, v73 offset:45056
	v_add_f32_dpp v64, v64, v64 row_mirror row_mask:0xf bank_mask:0xf bound_ctrl:1
	v_pk_fma_f32 v[60:61], v[224:225], v[64:65], v[60:61] op_sel_hi:[1,0,1] neg_lo:[1,0,0] neg_hi:[1,0,0]
	v_pk_fma_f32 v[62:63], v[226:227], v[64:65], v[62:63] op_sel_hi:[1,0,1] neg_lo:[1,0,0] neg_hi:[1,0,0]
	ds_read_b128 v[224:227], v72 offset:44288
	v_pk_mul_f32 v[66:67], v[232:233], v[60:61]
	v_pk_fma_f32 v[66:67], v[234:235], v[62:63], v[66:67]
	ds_read_b128 v[232:235], v72 offset:44800
	v_add_f32_e32 v150, v66, v67
	s_waitcnt lgkmcnt(6)
	v_pk_mul_f32 v[64:65], v[60:61], v[122:123]
	v_pk_fma_f32 v[64:65], v[62:63], v[124:125], v[64:65]
	v_add_f32_e32 v64, v64, v65
	v_pk_mul_f32 v[60:61], v[60:61], v[118:119]
	v_pk_mul_f32 v[62:63], v[62:63], v[120:121]
	v_add_f32_dpp v64, v64, v64 quad_perm:[1,0,3,2] row_mask:0xf bank_mask:0xf bound_ctrl:1
	v_pk_fma_f32 v[60:61], v[138:139], v[130:131], v[60:61] op_sel_hi:[0,1,1]
	v_pk_fma_f32 v[62:63], v[138:139], v[132:133], v[62:63] op_sel_hi:[0,1,1]
	v_add_f32_dpp v64, v64, v64 quad_perm:[2,3,0,1] row_mask:0xf bank_mask:0xf bound_ctrl:1
	ds_read_b128 v[122:125], v72 offset:45568
	ds_read_b128 v[118:121], v72 offset:45312
	v_add_f32_dpp v64, v64, v64 row_half_mirror row_mask:0xf bank_mask:0xf bound_ctrl:1
	ds_read_b128 v[130:133], v72 offset:46080
	ds_read_b32 v138, v73 offset:46592
	v_add_f32_dpp v64, v64, v64 row_mirror row_mask:0xf bank_mask:0xf bound_ctrl:1
	v_pk_fma_f32 v[60:61], v[126:127], v[64:65], v[60:61] op_sel_hi:[1,0,1] neg_lo:[1,0,0] neg_hi:[1,0,0]
	v_pk_fma_f32 v[62:63], v[128:129], v[64:65], v[62:63] op_sel_hi:[1,0,1] neg_lo:[1,0,0] neg_hi:[1,0,0]
	ds_read_b128 v[126:129], v72 offset:45824
	v_pk_mul_f32 v[66:67], v[134:135], v[60:61]
	v_pk_fma_f32 v[66:67], v[136:137], v[62:63], v[66:67]
	ds_read_b128 v[134:137], v72 offset:46336
	v_add_f32_e32 v151, v66, v67
	s_waitcnt lgkmcnt(6)
; template <bool DUAL>
; __device__ __forceinline__ void rwkv_tile(const Params& p, int l, int tile, unsigned char* smem) {
;     ...
; #pragma unroll 2
;       for (int i = 0; i < 32; ++i) {
;         const int inx = (i + 1) & 31;
;         const float4 nw4 = *(const float4*)(rp + inx * 384), nkk4 = *(const float4*)(rp + inx * 384 + 64), nkb4 = *(const float4*)(rp + inx * 384 + 128);
;         const float4 nkd4 = *(const float4*)(rp + inx * 384 + 192), nr4 = *(const float4*)(rp + inx * 384 + 256);
;         const float nv = vp[inx * 384];
;         v2f t = sA * (v2f){kk4.x, kk4.y};
;         t = sB * (v2f){kk4.z, kk4.w} + t;
;         float sa = t.x + t.y, ia = 0.f;
;         if (DUAL) {
;           v2f ti = iA * (v2f){kk4.x, kk4.y};
;           ti = iB * (v2f){kk4.z, kk4.w} + ti;
;           ia = ti.x + ti.y;
;           sa += dppf<0xB1>(sa); ia += dppf<0xB1>(ia);
;           sa += dppf<0x4E>(sa); ia += dppf<0x4E>(ia);
;           sa += dppf<0x141>(sa); ia += dppf<0x141>(ia);
;           sa += dppf<0x140>(sa); ia += dppf<0x140>(ia);
;         } else {
;           sa = sum16(sa);
;         }
;         v2f cA = sA * (v2f){w4.x, w4.y} + (v2f){kd4.x, kd4.y} * v;
;         v2f cB = sB * (v2f){w4.z, w4.w} + (v2f){kd4.z, kd4.w} * v;
;         sA = cA - (v2f){kb4.x, kb4.y} * sa;
;         sB = cB - (v2f){kb4.z, kb4.w} * sa;
;         v2f u = sA * (v2f){r4.x, r4.y};
;         u = sB * (v2f){r4.z, r4.w} + u;
;         float y = u.x + u.y, g = 0.f;
;         if (DUAL) {
;           iA = iA * (v2f){w4.x, w4.y} - (v2f){kb4.x, kb4.y} * ia;
;           iB = iB * (v2f){w4.z, w4.w} - (v2f){kb4.z, kb4.w} * ia;
;           v2f ui = iA * (v2f){r4.x, r4.y};
;           ui = iB * (v2f){r4.z, r4.w} + ui;
;           g = ui.x + ui.y;
;           y += dppf<0xB1>(y); g += dppf<0xB1>(g);
;           y += dppf<0x4E>(y); g += dppf<0x4E>(g);
;           y += dppf<0x141>(y); g += dppf<0x141>(g);
;           y += dppf<0x140>(y); g += dppf<0x140>(g);
;           if (fr == (i & 15)) gkeep = g;
;         } else {
;           y = sum16(y);
;         }
;         if (fr == (i & 15)) ykeep = y;
	v_pk_mul_f32 v[64:65], v[60:61], v[220:221]
	v_pk_fma_f32 v[64:65], v[62:63], v[222:223], v[64:65]
	v_add_f32_e32 v64, v64, v65
	v_pk_mul_f32 v[60:61], v[60:61], v[216:217]
	v_pk_mul_f32 v[62:63], v[62:63], v[218:219]
	v_add_f32_dpp v64, v64, v64 quad_perm:[1,0,3,2] row_mask:0xf bank_mask:0xf bound_ctrl:1
	v_pk_fma_f32 v[60:61], v[236:237], v[228:229], v[60:61] op_sel_hi:[0,1,1]
	v_pk_fma_f32 v[62:63], v[236:237], v[230:231], v[62:63] op_sel_hi:[0,1,1]
	v_add_f32_dpp v64, v64, v64 quad_perm:[2,3,0,1] row_mask:0xf bank_mask:0xf bound_ctrl:1
	ds_read_b128 v[220:223], v72 offset:47104
	ds_read_b128 v[216:219], v72 offset:46848
	v_add_f32_dpp v64, v64, v64 row_half_mirror row_mask:0xf bank_mask:0xf bound_ctrl:1
	ds_read_b128 v[228:231], v72 offset:47616
	ds_read_b32 v236, v73 offset:48128
	v_add_f32_dpp v64, v64, v64 row_mirror row_mask:0xf bank_mask:0xf bound_ctrl:1
	v_pk_fma_f32 v[60:61], v[224:225], v[64:65], v[60:61] op_sel_hi:[1,0,1] neg_lo:[1,0,0] neg_hi:[1,0,0]
	v_pk_fma_f32 v[62:63], v[226:227], v[64:65], v[62:63] op_sel_hi:[1,0,1] neg_lo:[1,0,0] neg_hi:[1,0,0]
	ds_read_b128 v[224:227], v72 offset:47360
	v_pk_mul_f32 v[66:67], v[232:233], v[60:61]
	v_pk_fma_f32 v[66:67], v[234:235], v[62:63], v[66:67]
	ds_read_b128 v[232:235], v72 offset:47872
	v_add_f32_e32 v152, v66, v67
	s_waitcnt lgkmcnt(6)
	v_pk_mul_f32 v[64:65], v[60:61], v[122:123]
	v_pk_fma_f32 v[64:65], v[62:63], v[124:125], v[64:65]
	v_add_f32_e32 v64, v64, v65
	v_pk_mul_f32 v[60:61], v[60:61], v[118:119]
	v_pk_mul_f32 v[62:63], v[62:63], v[120:121]
	v_add_f32_dpp v64, v64, v64 quad_perm:[1,0,3,2] row_mask:0xf bank_mask:0xf bound_ctrl:1
	v_pk_fma_f32 v[60:61], v[138:139], v[130:131], v[60:61] op_sel_hi:[0,1,1]
	v_pk_fma_f32 v[62:63], v[138:139], v[132:133], v[62:63] op_sel_hi:[0,1,1]
	v_add_f32_dpp v64, v64, v64 quad_perm:[2,3,0,1] row_mask:0xf bank_mask:0xf bound_ctrl:1
	ds_read_b128 v[122:125], v72 offset:48640
	ds_read_b128 v[118:121], v72 offset:48384
	v_add_f32_dpp v64, v64, v64 row_half_mirror row_mask:0xf bank_mask:0xf bound_ctrl:1
	ds_read_b128 v[130:133], v72 offset:49152
	ds_read_b32 v138, v73 offset:49664
	v_add_f32_dpp v64, v64, v64 row_mirror row_mask:0xf bank_mask:0xf bound_ctrl:1
	v_pk_fma_f32 v[60:61], v[126:127], v[64:65], v[60:61] op_sel_hi:[1,0,1] neg_lo:[1,0,0] neg_hi:[1,0,0]
	v_pk_fma_f32 v[62:63], v[128:129], v[64:65], v[62:63] op_sel_hi:[1,0,1] neg_lo:[1,0,0] neg_hi:[1,0,0]
	ds_read_b128 v[126:129], v72 offset:48896
	v_pk_mul_f32 v[66:67], v[134:135], v[60:61]
	v_pk_fma_f32 v[66:67], v[136:137], v[62:63], v[66:67]
	ds_read_b128 v[134:137], v72 offset:49408
	v_add_f32_e32 v153, v66, v67
	s_waitcnt lgkmcnt(6)
	v_pk_mul_f32 v[64:65], v[60:61], v[220:221]
	v_pk_fma_f32 v[64:65], v[62:63], v[222:223], v[64:65]
	v_add_f32_e32 v64, v64, v65
	v_pk_mul_f32 v[60:61], v[60:61], v[216:217]
	v_pk_mul_f32 v[62:63], v[62:63], v[218:219]
	v_add_f32_dpp v64, v64, v64 quad_perm:[1,0,3,2] row_mask:0xf bank_mask:0xf bound_ctrl:1
	v_pk_fma_f32 v[60:61], v[236:237], v[228:229], v[60:61] op_sel_hi:[0,1,1]
	v_pk_fma_f32 v[62:63], v[236:237], v[230:231], v[62:63] op_sel_hi:[0,1,1]
	v_add_f32_dpp v64, v64, v64 quad_perm:[2,3,0,1] row_mask:0xf bank_mask:0xf bound_ctrl:1
	ds_read_b128 v[220:223], v68 offset:25600
	ds_read_b128 v[216:219], v68 offset:25344
	v_add_f32_dpp v64, v64, v64 row_half_mirror row_mask:0xf bank_mask:0xf bound_ctrl:1
	ds_read_b128 v[228:231], v68 offset:26112
	ds_read_b32 v236, v69 offset:26624
	v_add_f32_dpp v64, v64, v64 row_mirror row_mask:0xf bank_mask:0xf bound_ctrl:1
	v_pk_fma_f32 v[60:61], v[224:225], v[64:65], v[60:61] op_sel_hi:[1,0,1] neg_lo:[1,0,0] neg_hi:[1,0,0]
	v_pk_fma_f32 v[62:63], v[226:227], v[64:65], v[62:63] op_sel_hi:[1,0,1] neg_lo:[1,0,0] neg_hi:[1,0,0]
	ds_read_b128 v[224:227], v68 offset:25856
	v_pk_mul_f32 v[66:67], v[232:233], v[60:61]
	v_pk_fma_f32 v[66:67], v[234:235], v[62:63], v[66:67]
	ds_read_b128 v[232:235], v68 offset:26368
	v_add_f32_e32 v154, v66, v67
	s_waitcnt lgkmcnt(6)
; __device__ __forceinline__ bf16_t f2bf(float f) { return (bf16_t)(pack2(f, 0.f) & 0xffffu); }
; template <bool DUAL>
; __device__ __forceinline__ void rwkv_tile(const Params& p, int l, int tile, unsigned char* smem) {
;     ...
;           sa = sum16(sa);
;         }
;         v2f cA = sA * (v2f){w4.x, w4.y} + (v2f){kd4.x, kd4.y} * v;
;         v2f cB = sB * (v2f){w4.z, w4.w} + (v2f){kd4.z, kd4.w} * v;
;         sA = cA - (v2f){kb4.x, kb4.y} * sa;
;         sB = cB - (v2f){kb4.z, kb4.w} * sa;
;         v2f u = sA * (v2f){r4.x, r4.y};
;         u = sB * (v2f){r4.z, r4.w} + u;
;         float y = u.x + u.y, g = 0.f;
;         if (DUAL) {
;           iA = iA * (v2f){w4.x, w4.y} - (v2f){kb4.x, kb4.y} * ia;
;           iB = iB * (v2f){w4.z, w4.w} - (v2f){kb4.z, kb4.w} * ia;
;           v2f ui = iA * (v2f){r4.x, r4.y};
;           ui = iB * (v2f){r4.z, r4.w} + ui;
;           g = ui.x + ui.y;
;           y += dppf<0xB1>(y); g += dppf<0xB1>(g);
;           y += dppf<0x4E>(y); g += dppf<0x4E>(g);
;           y += dppf<0x141>(y); g += dppf<0x141>(g);
;           y += dppf<0x140>(y); g += dppf<0x140>(g);
;           if (fr == (i & 15)) gkeep = g;
;         } else {
;           y = sum16(y);
;         }
;         if (fr == (i & 15)) ykeep = y;
;         if ((i & 15) == 15) {
;           const int ii = (i & 16) + fr;
;           const int ri = (d == 0) ? ii + 1 : 32 - ii;
;           const int pi = plo - 1 + ri;
;           p.yR[((size_t)d * TOK + rowbase + pi) * 256 + h * 64 + row] = f2bf(ykeep);
;           if (DUAL) p.GID[((size_t)(d * 4 + b) * NSEG1 + (cix - CSPLIT) * 32 + ii) * 256 + h * 64 + row] = f2bf(gkeep);
;         }
;         w4 = nw4; kk4 = nkk4; kb4 = nkb4; kd4 = nkd4; r4 = nr4; v = nv;
	v_pk_mul_f32 v[64:65], v[60:61], v[122:123]
	v_pk_fma_f32 v[64:65], v[62:63], v[124:125], v[64:65]
	v_add_f32_e32 v64, v64, v65
	v_pk_mul_f32 v[60:61], v[60:61], v[118:119]
	v_pk_mul_f32 v[62:63], v[62:63], v[120:121]
	v_add_f32_dpp v64, v64, v64 quad_perm:[1,0,3,2] row_mask:0xf bank_mask:0xf bound_ctrl:1
	v_pk_fma_f32 v[60:61], v[138:139], v[130:131], v[60:61] op_sel_hi:[0,1,1]
	v_pk_fma_f32 v[62:63], v[138:139], v[132:133], v[62:63] op_sel_hi:[0,1,1]
	v_add_f32_dpp v64, v64, v64 quad_perm:[2,3,0,1] row_mask:0xf bank_mask:0xf bound_ctrl:1
	ds_read_b128 v[122:125], v68 offset:27136
	ds_read_b128 v[118:121], v68 offset:26880
	v_add_f32_dpp v64, v64, v64 row_half_mirror row_mask:0xf bank_mask:0xf bound_ctrl:1
	ds_read_b128 v[130:133], v68 offset:27648
	ds_read_b32 v138, v69 offset:28160
	v_add_f32_dpp v64, v64, v64 row_mirror row_mask:0xf bank_mask:0xf bound_ctrl:1
	v_pk_fma_f32 v[60:61], v[126:127], v[64:65], v[60:61] op_sel_hi:[1,0,1] neg_lo:[1,0,0] neg_hi:[1,0,0]
	v_pk_fma_f32 v[62:63], v[128:129], v[64:65], v[62:63] op_sel_hi:[1,0,1] neg_lo:[1,0,0] neg_hi:[1,0,0]
	ds_read_b128 v[126:129], v68 offset:27392
	v_pk_mul_f32 v[66:67], v[134:135], v[60:61]
	v_pk_fma_f32 v[66:67], v[136:137], v[62:63], v[66:67]
	ds_read_b128 v[134:137], v68 offset:27904
	v_add_f32_e32 v155, v66, v67
	v_add_f32_dpp v140, v140, v140 row_shl:8 row_mask:0xf bank_mask:0x3
	v_add_f32_dpp v140, v148, v148 row_shr:8 row_mask:0xf bank_mask:0xc
	v_add_f32_dpp v141, v141, v141 row_shl:8 row_mask:0xf bank_mask:0x3
	v_add_f32_dpp v141, v149, v149 row_shr:8 row_mask:0xf bank_mask:0xc
	v_add_f32_dpp v142, v142, v142 row_shl:8 row_mask:0xf bank_mask:0x3
	v_add_f32_dpp v142, v150, v150 row_shr:8 row_mask:0xf bank_mask:0xc
	v_add_f32_dpp v143, v143, v143 row_shl:8 row_mask:0xf bank_mask:0x3
	v_add_f32_dpp v143, v151, v151 row_shr:8 row_mask:0xf bank_mask:0xc
	v_add_f32_dpp v144, v144, v144 row_shl:8 row_mask:0xf bank_mask:0x3
	v_add_f32_dpp v144, v152, v152 row_shr:8 row_mask:0xf bank_mask:0xc
	v_add_f32_dpp v145, v145, v145 row_shl:8 row_mask:0xf bank_mask:0x3
	v_add_f32_dpp v145, v153, v153 row_shr:8 row_mask:0xf bank_mask:0xc
	v_add_f32_dpp v146, v146, v146 row_shl:8 row_mask:0xf bank_mask:0x3
	v_add_f32_dpp v146, v154, v154 row_shr:8 row_mask:0xf bank_mask:0xc
	v_add_f32_dpp v147, v147, v147 row_shl:8 row_mask:0xf bank_mask:0x3
	v_add_f32_dpp v147, v155, v155 row_shr:8 row_mask:0xf bank_mask:0xc
	v_add_f32_dpp v140, v140, v140 row_shl:4 row_mask:0xf bank_mask:0x5
	v_add_f32_dpp v140, v144, v144 row_shr:4 row_mask:0xf bank_mask:0xa
	v_add_f32_dpp v141, v141, v141 row_shl:4 row_mask:0xf bank_mask:0x5
	v_add_f32_dpp v141, v145, v145 row_shr:4 row_mask:0xf bank_mask:0xa
	v_add_f32_dpp v142, v142, v142 row_shl:4 row_mask:0xf bank_mask:0x5
	v_add_f32_dpp v142, v146, v146 row_shr:4 row_mask:0xf bank_mask:0xa
	v_add_f32_dpp v143, v143, v143 row_shl:4 row_mask:0xf bank_mask:0x5
	v_add_f32_dpp v143, v147, v147 row_shr:4 row_mask:0xf bank_mask:0xa
	v_cndmask_b32_e32 v156, v140, v142, vcc
	v_cndmask_b32_e32 v157, v142, v140, vcc
	v_cndmask_b32_e32 v159, v143, v141, vcc
	v_cndmask_b32_e32 v158, v141, v143, vcc
	v_add_f32_dpp v156, v157, v156 quad_perm:[2,3,0,1] row_mask:0xf bank_mask:0xf
	v_add_f32_dpp v158, v159, v158 quad_perm:[2,3,0,1] row_mask:0xf bank_mask:0xf
	v_cndmask_b32_e64 v160, v156, v158, s[100:101]
	v_cndmask_b32_e64 v161, v158, v156, s[100:101]
	v_add_u32_e32 v72, 0x6000, v72
	v_add_u32_e32 v73, 0x6000, v73
	v_add_f32_dpp v70, v161, v160 quad_perm:[1,0,3,2] row_mask:0xf bank_mask:0xf
	v_mov_b32_e32 v68, v99
	v_mov_b32_e32 v69, v100
	v_mov_b32_e32 v77, v71
	v_add_u32_e32 v75, 1, v77
	v_sub_u32_e32 v74, 32, v77
	v_cndmask_b32_e64 v74, v74, v75, s[36:37]
	v_add_u32_e32 v74, s28, v74
	v_ashrrev_i32_e32 v75, 31, v74
	v_lshl_add_u64 v[74:75], s[20:21], 0, v[74:75]
	v_lshlrev_b64 v[74:75], 9, v[74:75]
	v_cvt_pk_bf16_f32 v76, v70, v70
	v_lshl_add_u64 v[74:75], v[90:91], 0, v[74:75]
	global_store_short v[74:75], v76, off
	v_add_u32_e32 v71, 16, v71
	s_add_i32 s50, s50, 1
	s_cmp_lg_u32 s50, 2
	s_cbranch_scc1 .Lrw_nd_loop
	s_branch .LBB0_1491

; __global__ void __launch_bounds__(NTHREADS, LBW) mega(Params p, int ph_lo, int ph_hi) {
;   extern __shared__ __attribute__((aligned(16))) unsigned char smem[];
	.amdhsa_kernel _Z4mega6Paramsii
		.amdhsa_group_segment_fixed_size 0
		.amdhsa_private_segment_fixed_size 0
		.amdhsa_kernarg_size 664
		.amdhsa_user_sgpr_count 2
		.amdhsa_user_sgpr_dispatch_ptr 0
		.amdhsa_user_sgpr_queue_ptr 0
		.amdhsa_user_sgpr_kernarg_segment_ptr 1
		.amdhsa_user_sgpr_dispatch_id 0
		.amdhsa_user_sgpr_kernarg_preload_length 0
		.amdhsa_user_sgpr_kernarg_preload_offset 0
		.amdhsa_user_sgpr_private_segment_size 0
		.amdhsa_uses_dynamic_stack 0
		.amdhsa_enable_private_segment 0
		.amdhsa_system_sgpr_workgroup_id_x 1
		.amdhsa_system_sgpr_workgroup_id_y 0
		.amdhsa_system_sgpr_workgroup_id_z 0
		.amdhsa_system_sgpr_workgroup_info 0
		.amdhsa_system_vgpr_workitem_id 2
		.amdhsa_next_free_vgpr 256
		.amdhsa_next_free_sgpr 102
		.amdhsa_accum_offset 256
		.amdhsa_reserve_vcc 1
		.amdhsa_float_round_mode_32 0
		.amdhsa_float_round_mode_16_64 0
		.amdhsa_float_denorm_mode_32 3
		.amdhsa_float_denorm_mode_16_64 3
		.amdhsa_dx10_clamp 1
		.amdhsa_ieee_mode 1
		.amdhsa_fp16_overflow 0
		.amdhsa_tg_split 0
		.amdhsa_exception_fp_ieee_invalid_op 0
		.amdhsa_exception_fp_denorm_src 0
		.amdhsa_exception_fp_ieee_div_zero 0
		.amdhsa_exception_fp_ieee_overflow 0
		.amdhsa_exception_fp_ieee_underflow 0
		.amdhsa_exception_fp_ieee_inexact 0
		.amdhsa_exception_int_div_zero 0
	.end_amdhsa_kernel

; __global__ void __launch_bounds__(NTHREADS, LBW) mega(Params p, int ph_lo, int ph_hi) {
;   extern __shared__ __attribute__((aligned(16))) unsigned char smem[];
amdhsa.kernels:
  - .agpr_count:     0
    .args:
      - .offset:         0
        .size:           400
        .value_kind:     by_value
      - .offset:         400
        .size:           4
        .value_kind:     by_value
      - .offset:         404
        .size:           4
        .value_kind:     by_value
      - .offset:         408
        .size:           4
        .value_kind:     hidden_block_count_x
      - .offset:         412
        .size:           4
        .value_kind:     hidden_block_count_y
      - .offset:         416
        .size:           4
        .value_kind:     hidden_block_count_z
      - .offset:         420
        .size:           2
        .value_kind:     hidden_group_size_x
      - .offset:         422
        .size:           2
        .value_kind:     hidden_group_size_y
      - .offset:         424
        .size:           2
        .value_kind:     hidden_group_size_z
      - .offset:         426
        .size:           2
        .value_kind:     hidden_remainder_x
      - .offset:         428
        .size:           2
        .value_kind:     hidden_remainder_y
      - .offset:         430
        .size:           2
        .value_kind:     hidden_remainder_z
      - .offset:         448
        .size:           8
        .value_kind:     hidden_global_offset_x
      - .offset:         456
        .size:           8
        .value_kind:     hidden_global_offset_y
      - .offset:         464
        .size:           8
        .value_kind:     hidden_global_offset_z
      - .offset:         472
        .size:           2
        .value_kind:     hidden_grid_dims
      - .offset:         496
        .size:           8
        .value_kind:     hidden_multigrid_sync_arg
      - .offset:         528
        .size:           4
        .value_kind:     hidden_dynamic_lds_size
    .group_segment_fixed_size: 0
    .kernarg_segment_align: 8
    .kernarg_segment_size: 664
    .language:       OpenCL C
    .language_version:
      - 2
      - 0
    .max_flat_workgroup_size: 256
    .name:           _Z4mega6Paramsii
    .private_segment_fixed_size: 0
    .sgpr_count:     108
    .sgpr_spill_count: 321
    .symbol:         _Z4mega6Paramsii.kd
    .uniform_work_group_size: 1
    .uses_dynamic_stack: false
    .vgpr_count:     256
    .vgpr_spill_count: 0
    .wavefront_size: 64
